# baseline (speedup 1.0000x reference)
; __device__ __forceinline__ unsigned cvt_pk_bf16(float lo, float hi) { unsigned r; asm volatile("v_cvt_pk_bf16_f32 %0, %1, %2" : "=v"(r) : "v"(lo), "v"(hi)); return r; }
;     __device__ __forceinline__ void operator()(const f32x4 (&acc)[2][2][4][2], const Unit& u, int wr, int wc, int fr, int fq) const {
;         const int row0 = u.pm * BM + wr * 64 + fr; const int fcol0 = u.pn * 128 + wc * 16 + 4 * fq;
; #pragma unroll
;         for (int ai = 0; ai < 2; ++ai)
; #pragma unroll
;             for (int m = 0; m < 4; ++m) {
;                 const int row = row0 + ai * HALF + m * 16; const float rs = rsqrtf(sumsq[row] * inv_n + eps);
; #pragma unroll
;                 for (int bj = 0; bj < 2; ++bj) {
;                     const f32x4 g = acc[ai][bj][m][0] * rs, up = acc[ai][bj][m][1] * rs; f32x4 a;
; #pragma unroll
;                     for (int e = 0; e < 4; ++e) a[e] = g[e] * __builtin_amdgcn_rcpf(1.f + __builtin_amdgcn_exp2f(-1.4426950408889634f * g[e])) * up[e];
;                     u32x2 w; w.x = cvt_pk_bf16(a[0], a[1]); w.y = cvt_pk_bf16(a[2], a[3]);
;                     *(u32x2*)(O + (size_t)row * ldo + fcol0 + bj * 64) = w;
;                 }
.LBB0_353:
	v_lshl_add_u32 v144, s8, 8, v148
	v_ashrrev_i32_e32 v145, 31, v144
	v_lshl_add_u64 v[146:147], v[144:145], 2, s[18:19]
	global_load_dword v145, v[146:147], off
	global_load_dword v249, v[146:147], off offset:64
	global_load_dword v250, v[146:147], off offset:128
	global_load_dword v251, v[146:147], off offset:192
	global_load_dword v252, v[146:147], off offset:512
	global_load_dword v253, v[146:147], off offset:576
	global_load_dword v254, v[146:147], off offset:640
	global_load_dword v255, v[146:147], off offset:704
	v_lshl_or_b32 v156, s9, 7, v150
	v_ashrrev_i32_e32 v157, 31, v156
	v_mov_b32_e32 v160, v126
	v_mov_b32_e32 v161, v122
	v_mov_b32_e32 v122, v127
	v_mov_b32_e32 v126, v116
	v_mov_b32_e32 v127, v112
	v_mov_b32_e32 v112, v117
	v_lshlrev_b64 v[116:117], 1, v[156:157]
	v_or_b32_e32 v164, 16, v144
	v_ashrrev_i32_e32 v165, 31, v164
	v_mov_b32_e32 v158, v124
	v_mov_b32_e32 v159, v120
	v_mov_b32_e32 v120, v125
	v_mov_b32_e32 v162, v118
	v_mov_b32_e32 v163, v114
	v_mov_b32_e32 v114, v119
	v_mov_b64_e32 v[124:125], s[10:11]
	v_mad_i64_i32 v[118:119], s[4:5], v144, s53, v[124:125]
	v_lshl_add_u64 v[118:119], v[118:119], 0, v[116:117]
	s_waitcnt vmcnt(0)
	v_fmamk_f32 v145, v145, 0x3a000000, v155
	v_mul_f32_e32 v156, 0x4b800000, v145
	v_cmp_gt_f32_e32 vcc, s52, v145
	s_nop 1
	v_cndmask_b32_e32 v145, v145, v156, vcc
	v_rsq_f32_e32 v145, v145
	v_lshl_add_u64 v[156:157], v[164:165], 2, s[18:19]
	v_mul_f32_e32 v165, 0x45800000, v145
	v_cndmask_b32_e32 v166, v145, v165, vcc
	v_pk_mul_f32 v[158:159], v[158:159], v[166:167] op_sel_hi:[1,0]
	v_pk_mul_f32 v[120:121], v[120:121], v[166:167] op_sel_hi:[1,0]
	v_pk_mul_f32 v[160:161], v[160:161], v[166:167] op_sel_hi:[1,0]
	v_pk_mul_f32 v[122:123], v[122:123], v[166:167] op_sel_hi:[1,0]
	v_pk_mul_f32 v[126:127], v[126:127], v[166:167] op_sel_hi:[1,0]
	v_pk_mul_f32 v[112:113], v[112:113], v[166:167] op_sel_hi:[1,0]
	v_pk_mul_f32 v[162:163], v[162:163], v[166:167] op_sel_hi:[1,0]
	v_pk_mul_f32 v[114:115], v[114:115], v[166:167] op_sel_hi:[1,0]
	v_mul_f32_e32 v145, 0xbfb8aa3b, v159
	v_mul_f32_e32 v165, 0xbfb8aa3b, v121
	v_mul_f32_e32 v166, 0xbfb8aa3b, v161
	v_mul_f32_e32 v167, 0xbfb8aa3b, v123
	v_mul_f32_e32 v168, 0xbfb8aa3b, v127
	v_mul_f32_e32 v169, 0xbfb8aa3b, v113
	v_mul_f32_e32 v170, 0xbfb8aa3b, v163
	v_mul_f32_e32 v171, 0xbfb8aa3b, v115
	v_exp_f32_e32 v145, v145
	v_exp_f32_e32 v165, v165
	v_exp_f32_e32 v166, v166
	v_exp_f32_e32 v167, v167
	v_exp_f32_e32 v168, v168
	v_exp_f32_e32 v169, v169
	v_exp_f32_e32 v170, v170
	v_exp_f32_e32 v171, v171
	v_add_f32_e32 v145, 1.0, v145
	v_add_f32_e32 v165, 1.0, v165
	v_add_f32_e32 v166, 1.0, v166
	v_add_f32_e32 v167, 1.0, v167
	v_add_f32_e32 v168, 1.0, v168
	v_add_f32_e32 v169, 1.0, v169
	v_add_f32_e32 v170, 1.0, v170
	v_add_f32_e32 v171, 1.0, v171
	v_rcp_f32_e32 v145, v145
	v_rcp_f32_e32 v165, v165
	v_rcp_f32_e32 v166, v166
	v_rcp_f32_e32 v167, v167
	v_rcp_f32_e32 v168, v168
	v_rcp_f32_e32 v169, v169
	v_rcp_f32_e32 v170, v170
	v_rcp_f32_e32 v171, v171
	v_mul_f32_e32 v145, v159, v145
	v_mul_f32_e32 v121, v121, v165
	v_mul_f32_e32 v159, v161, v166
	v_mul_f32_e32 v123, v123, v167
	v_mul_f32_e32 v127, v127, v168
	v_mul_f32_e32 v113, v113, v169
	v_mul_f32_e32 v161, v163, v170
	v_mul_f32_e32 v115, v115, v171
	v_mul_f32_e32 v145, v158, v145
	v_mul_f32_e32 v120, v120, v121
	v_mul_f32_e32 v121, v160, v159
	v_mul_f32_e32 v122, v122, v123
	v_mul_f32_e32 v123, v126, v127
	v_mul_f32_e32 v126, v112, v113
	v_cvt_pk_bf16_f32 v112, v145, v120
	v_cvt_pk_bf16_f32 v113, v121, v122
	v_mul_f32_e32 v127, v162, v161
	v_mul_f32_e32 v114, v114, v115
	global_store_dwordx2 v[118:119], v[112:113], off
	v_cvt_pk_bf16_f32 v112, v123, v126
	v_cvt_pk_bf16_f32 v113, v127, v114
	global_store_dwordx2 v[118:119], v[112:113], off offset:128
	s_nop 0
	v_mov_b32_e32 v113, v104
	v_mov_b32_e32 v104, v109
	v_mov_b32_e32 v109, v106
	v_mov_b32_e32 v106, v111
	v_mov_b32_e32 v111, v96
	v_mov_b32_e32 v96, v101
	v_mov_b32_e32 v101, v98
	v_mov_b32_e32 v98, v103
	v_mov_b32_e32 v112, v108
	v_mov_b32_e32 v108, v110
	v_mov_b32_e32 v110, v100
	v_mov_b32_e32 v100, v102
	v_or_b32_e32 v102, 32, v144
	v_mad_i64_i32 v[114:115], s[4:5], v164, s53, v[124:125]
	v_lshl_add_u64 v[114:115], v[114:115], 0, v[116:117]
	s_nop 1
	v_mov_b32_e32 v118, v249
	v_fmamk_f32 v103, v118, 0x3a000000, v155
	v_mul_f32_e32 v118, 0x4b800000, v103
	v_cmp_gt_f32_e32 vcc, s52, v103
	s_nop 1
	v_cndmask_b32_e32 v103, v103, v118, vcc
	v_rsq_f32_e32 v120, v103
	v_ashrrev_i32_e32 v103, 31, v102
	v_lshl_add_u64 v[118:119], v[102:103], 2, s[18:19]
	v_mul_f32_e32 v103, 0x45800000, v120
	v_cndmask_b32_e32 v120, v120, v103, vcc
	v_pk_mul_f32 v[112:113], v[112:113], v[120:121] op_sel_hi:[1,0]
	v_pk_mul_f32 v[104:105], v[104:105], v[120:121] op_sel_hi:[1,0]
	v_pk_mul_f32 v[108:109], v[108:109], v[120:121] op_sel_hi:[1,0]
	v_pk_mul_f32 v[106:107], v[106:107], v[120:121] op_sel_hi:[1,0]
	v_pk_mul_f32 v[96:97], v[96:97], v[120:121] op_sel_hi:[1,0]
	v_pk_mul_f32 v[110:111], v[110:111], v[120:121] op_sel_hi:[1,0]
	v_pk_mul_f32 v[100:101], v[100:101], v[120:121] op_sel_hi:[1,0]
	v_pk_mul_f32 v[98:99], v[98:99], v[120:121] op_sel_hi:[1,0]
	v_mul_f32_e32 v103, 0xbfb8aa3b, v113
	v_mul_f32_e32 v120, 0xbfb8aa3b, v105
	v_mul_f32_e32 v121, 0xbfb8aa3b, v109
	v_mul_f32_e32 v122, 0xbfb8aa3b, v107
	v_mul_f32_e32 v126, 0xbfb8aa3b, v97
	v_mul_f32_e32 v123, 0xbfb8aa3b, v111
	v_mul_f32_e32 v127, 0xbfb8aa3b, v101
	v_mul_f32_e32 v145, 0xbfb8aa3b, v99
	v_exp_f32_e32 v103, v103
	v_exp_f32_e32 v120, v120
	v_exp_f32_e32 v121, v121
	v_exp_f32_e32 v122, v122
	v_exp_f32_e32 v126, v126
	v_exp_f32_e32 v123, v123
	v_exp_f32_e32 v127, v127
	v_exp_f32_e32 v145, v145
; __device__ __forceinline__ unsigned cvt_pk_bf16(float lo, float hi) { unsigned r; asm volatile("v_cvt_pk_bf16_f32 %0, %1, %2" : "=v"(r) : "v"(lo), "v"(hi)); return r; }
;     __device__ __forceinline__ void operator()(const f32x4 (&acc)[2][2][4][2], const Unit& u, int wr, int wc, int fr, int fq) const {
;         const int row0 = u.pm * BM + wr * 64 + fr; const int fcol0 = u.pn * 128 + wc * 16 + 4 * fq;
; #pragma unroll
;         for (int ai = 0; ai < 2; ++ai)
; #pragma unroll
;             for (int m = 0; m < 4; ++m) {
;                 const int row = row0 + ai * HALF + m * 16; const float rs = rsqrtf(sumsq[row] * inv_n + eps);
; #pragma unroll
;                 for (int bj = 0; bj < 2; ++bj) {
;                     const f32x4 g = acc[ai][bj][m][0] * rs, up = acc[ai][bj][m][1] * rs; f32x4 a;
; #pragma unroll
;                     for (int e = 0; e < 4; ++e) a[e] = g[e] * __builtin_amdgcn_rcpf(1.f + __builtin_amdgcn_exp2f(-1.4426950408889634f * g[e])) * up[e];
;                     u32x2 w; w.x = cvt_pk_bf16(a[0], a[1]); w.y = cvt_pk_bf16(a[2], a[3]);
;                     *(u32x2*)(O + (size_t)row * ldo + fcol0 + bj * 64) = w;
;                 }
	v_add_f32_e32 v103, 1.0, v103
	v_add_f32_e32 v120, 1.0, v120
	v_add_f32_e32 v121, 1.0, v121
	v_add_f32_e32 v122, 1.0, v122
	v_add_f32_e32 v126, 1.0, v126
	v_add_f32_e32 v123, 1.0, v123
	v_add_f32_e32 v127, 1.0, v127
	v_add_f32_e32 v145, 1.0, v145
	v_rcp_f32_e32 v103, v103
	v_rcp_f32_e32 v120, v120
	v_rcp_f32_e32 v121, v121
	v_rcp_f32_e32 v122, v122
	v_rcp_f32_e32 v126, v126
	v_rcp_f32_e32 v123, v123
	v_rcp_f32_e32 v127, v127
	v_rcp_f32_e32 v145, v145
	v_mul_f32_e32 v103, v113, v103
	v_mul_f32_e32 v105, v105, v120
	v_mul_f32_e32 v109, v109, v121
	v_mul_f32_e32 v107, v107, v122
	v_mul_f32_e32 v97, v97, v126
	v_mul_f32_e32 v111, v111, v123
	v_mul_f32_e32 v101, v101, v127
	v_mul_f32_e32 v99, v99, v145
	v_mul_f32_e32 v103, v112, v103
	v_mul_f32_e32 v104, v104, v105
	v_mul_f32_e32 v105, v108, v109
	v_mul_f32_e32 v106, v106, v107
	v_mul_f32_e32 v108, v96, v97
	v_cvt_pk_bf16_f32 v96, v103, v104
	v_cvt_pk_bf16_f32 v97, v105, v106
	v_mul_f32_e32 v107, v110, v111
	v_mul_f32_e32 v100, v100, v101
	v_mul_f32_e32 v98, v98, v99
	global_store_dwordx2 v[114:115], v[96:97], off
	v_cvt_pk_bf16_f32 v96, v107, v108
	v_cvt_pk_bf16_f32 v97, v100, v98
	global_store_dwordx2 v[114:115], v[96:97], off offset:128
	s_nop 0
	v_mov_b32_e32 v97, v88
	v_mov_b32_e32 v88, v93
	v_mov_b32_e32 v93, v90
	v_mov_b32_e32 v90, v95
	v_mov_b32_e32 v95, v80
	v_mov_b32_e32 v80, v85
	v_mov_b32_e32 v85, v82
	v_mov_b32_e32 v82, v87
	v_mad_i64_i32 v[98:99], s[4:5], v102, s53, v[124:125]
	v_mov_b32_e32 v96, v92
	v_mov_b32_e32 v92, v94
	v_mov_b32_e32 v94, v84
	v_mov_b32_e32 v84, v86
	v_or_b32_e32 v86, 48, v144
	v_lshl_add_u64 v[98:99], v[98:99], 0, v[116:117]
	s_nop 1
	v_mov_b32_e32 v100, v250
	v_fmamk_f32 v87, v100, 0x3a000000, v155
	v_mul_f32_e32 v100, 0x4b800000, v87
	v_cmp_gt_f32_e32 vcc, s52, v87
	s_nop 1
	v_cndmask_b32_e32 v87, v87, v100, vcc
	v_rsq_f32_e32 v102, v87
	v_ashrrev_i32_e32 v87, 31, v86
	v_lshl_add_u64 v[100:101], v[86:87], 2, s[18:19]
	v_mul_f32_e32 v87, 0x45800000, v102
	v_cndmask_b32_e32 v102, v102, v87, vcc
	v_pk_mul_f32 v[96:97], v[96:97], v[102:103] op_sel_hi:[1,0]
	v_pk_mul_f32 v[88:89], v[88:89], v[102:103] op_sel_hi:[1,0]
	v_pk_mul_f32 v[92:93], v[92:93], v[102:103] op_sel_hi:[1,0]
	v_pk_mul_f32 v[90:91], v[90:91], v[102:103] op_sel_hi:[1,0]
	v_pk_mul_f32 v[80:81], v[80:81], v[102:103] op_sel_hi:[1,0]
	v_pk_mul_f32 v[94:95], v[94:95], v[102:103] op_sel_hi:[1,0]
	v_pk_mul_f32 v[84:85], v[84:85], v[102:103] op_sel_hi:[1,0]
	v_pk_mul_f32 v[82:83], v[82:83], v[102:103] op_sel_hi:[1,0]
	v_mul_f32_e32 v87, 0xbfb8aa3b, v97
	v_mul_f32_e32 v102, 0xbfb8aa3b, v89
	v_mul_f32_e32 v103, 0xbfb8aa3b, v93
	v_mul_f32_e32 v104, 0xbfb8aa3b, v91
	v_mul_f32_e32 v106, 0xbfb8aa3b, v81
	v_mul_f32_e32 v105, 0xbfb8aa3b, v95
	v_mul_f32_e32 v107, 0xbfb8aa3b, v85
	v_mul_f32_e32 v108, 0xbfb8aa3b, v83
	v_exp_f32_e32 v87, v87
	v_exp_f32_e32 v102, v102
	v_exp_f32_e32 v103, v103
	v_exp_f32_e32 v104, v104
	v_exp_f32_e32 v106, v106
	v_exp_f32_e32 v105, v105
	v_exp_f32_e32 v107, v107
	v_exp_f32_e32 v108, v108
	v_add_f32_e32 v87, 1.0, v87
	v_add_f32_e32 v102, 1.0, v102
	v_add_f32_e32 v103, 1.0, v103
	v_add_f32_e32 v104, 1.0, v104
	v_add_f32_e32 v106, 1.0, v106
	v_add_f32_e32 v105, 1.0, v105
	v_add_f32_e32 v107, 1.0, v107
	v_add_f32_e32 v108, 1.0, v108
	v_rcp_f32_e32 v87, v87
	v_rcp_f32_e32 v102, v102
	v_rcp_f32_e32 v103, v103
	v_rcp_f32_e32 v104, v104
	v_rcp_f32_e32 v106, v106
	v_rcp_f32_e32 v105, v105
	v_rcp_f32_e32 v107, v107
	v_rcp_f32_e32 v108, v108
	v_mul_f32_e32 v87, v97, v87
	v_mul_f32_e32 v89, v89, v102
	v_mul_f32_e32 v93, v93, v103
	v_mul_f32_e32 v91, v91, v104
	v_mul_f32_e32 v81, v81, v106
	v_mul_f32_e32 v95, v95, v105
	v_mul_f32_e32 v85, v85, v107
	v_mul_f32_e32 v83, v83, v108
	v_mul_f32_e32 v87, v96, v87
	v_mul_f32_e32 v88, v88, v89
	v_mul_f32_e32 v89, v92, v93
	v_mul_f32_e32 v90, v90, v91
	v_mul_f32_e32 v92, v80, v81
	v_cvt_pk_bf16_f32 v80, v87, v88
	v_cvt_pk_bf16_f32 v81, v89, v90
	v_mul_f32_e32 v91, v94, v95
	v_mul_f32_e32 v84, v84, v85
	v_mul_f32_e32 v82, v82, v83
	global_store_dwordx2 v[98:99], v[80:81], off
	v_cvt_pk_bf16_f32 v80, v91, v92
	v_cvt_pk_bf16_f32 v81, v84, v82
	global_store_dwordx2 v[98:99], v[80:81], off offset:128
	s_nop 0
	v_mov_b32_e32 v80, v76
	v_mov_b32_e32 v76, v78
	v_mov_b32_e32 v78, v68
	v_mov_b32_e32 v68, v70
	v_mov_b32_e32 v81, v72
	v_mov_b32_e32 v72, v77
	v_mov_b32_e32 v77, v74
	v_mov_b32_e32 v74, v79
	v_mov_b32_e32 v79, v64
	v_mov_b32_e32 v64, v69
	v_mov_b32_e32 v69, v66
	v_mov_b32_e32 v66, v71
	s_nop 1
	v_mov_b32_e32 v82, v251
	v_fmamk_f32 v70, v82, 0x3a000000, v155
	v_mul_f32_e32 v71, 0x4b800000, v70
	v_cmp_gt_f32_e32 vcc, s52, v70
	s_nop 1
	v_cndmask_b32_e32 v70, v70, v71, vcc
	v_rsq_f32_e32 v82, v70
	v_mad_i64_i32 v[70:71], s[4:5], v86, s53, v[124:125]
	v_lshl_add_u64 v[70:71], v[70:71], 0, v[116:117]
	v_mul_f32_e32 v83, 0x45800000, v82
	v_cndmask_b32_e32 v82, v82, v83, vcc
	v_pk_mul_f32 v[80:81], v[80:81], v[82:83] op_sel_hi:[1,0]
	v_pk_mul_f32 v[72:73], v[72:73], v[82:83] op_sel_hi:[1,0]
	v_pk_mul_f32 v[76:77], v[76:77], v[82:83] op_sel_hi:[1,0]
	v_pk_mul_f32 v[74:75], v[74:75], v[82:83] op_sel_hi:[1,0]
	v_pk_mul_f32 v[64:65], v[64:65], v[82:83] op_sel_hi:[1,0]
	v_pk_mul_f32 v[78:79], v[78:79], v[82:83] op_sel_hi:[1,0]
	v_pk_mul_f32 v[68:69], v[68:69], v[82:83] op_sel_hi:[1,0]
	v_pk_mul_f32 v[66:67], v[66:67], v[82:83] op_sel_hi:[1,0]
	v_mul_f32_e32 v82, 0xbfb8aa3b, v81
	v_mul_f32_e32 v83, 0xbfb8aa3b, v73
	v_mul_f32_e32 v84, 0xbfb8aa3b, v77
	v_mul_f32_e32 v85, 0xbfb8aa3b, v75
	v_mul_f32_e32 v87, 0xbfb8aa3b, v65
	v_mul_f32_e32 v86, 0xbfb8aa3b, v79
	v_mul_f32_e32 v88, 0xbfb8aa3b, v69
	v_mul_f32_e32 v89, 0xbfb8aa3b, v67
	v_exp_f32_e32 v82, v82
; __device__ __forceinline__ unsigned cvt_pk_bf16(float lo, float hi) { unsigned r; asm volatile("v_cvt_pk_bf16_f32 %0, %1, %2" : "=v"(r) : "v"(lo), "v"(hi)); return r; }
;     __device__ __forceinline__ void operator()(const f32x4 (&acc)[2][2][4][2], const Unit& u, int wr, int wc, int fr, int fq) const {
;         const int row0 = u.pm * BM + wr * 64 + fr; const int fcol0 = u.pn * 128 + wc * 16 + 4 * fq;
; #pragma unroll
;         for (int ai = 0; ai < 2; ++ai)
; #pragma unroll
;             for (int m = 0; m < 4; ++m) {
;                 const int row = row0 + ai * HALF + m * 16; const float rs = rsqrtf(sumsq[row] * inv_n + eps);
; #pragma unroll
;                 for (int bj = 0; bj < 2; ++bj) {
;                     const f32x4 g = acc[ai][bj][m][0] * rs, up = acc[ai][bj][m][1] * rs; f32x4 a;
; #pragma unroll
;                     for (int e = 0; e < 4; ++e) a[e] = g[e] * __builtin_amdgcn_rcpf(1.f + __builtin_amdgcn_exp2f(-1.4426950408889634f * g[e])) * up[e];
;                     u32x2 w; w.x = cvt_pk_bf16(a[0], a[1]); w.y = cvt_pk_bf16(a[2], a[3]);
;                     *(u32x2*)(O + (size_t)row * ldo + fcol0 + bj * 64) = w;
;                 }
	v_exp_f32_e32 v83, v83
	v_exp_f32_e32 v84, v84
	v_exp_f32_e32 v85, v85
	v_exp_f32_e32 v87, v87
	v_exp_f32_e32 v86, v86
	v_exp_f32_e32 v88, v88
	v_exp_f32_e32 v89, v89
	v_add_f32_e32 v82, 1.0, v82
	v_add_f32_e32 v83, 1.0, v83
	v_add_f32_e32 v84, 1.0, v84
	v_add_f32_e32 v85, 1.0, v85
	v_add_f32_e32 v87, 1.0, v87
	v_add_f32_e32 v86, 1.0, v86
	v_add_f32_e32 v88, 1.0, v88
	v_add_f32_e32 v89, 1.0, v89
	v_rcp_f32_e32 v82, v82
	v_rcp_f32_e32 v83, v83
	v_rcp_f32_e32 v84, v84
	v_rcp_f32_e32 v85, v85
	v_rcp_f32_e32 v87, v87
	v_rcp_f32_e32 v86, v86
	v_rcp_f32_e32 v88, v88
	v_rcp_f32_e32 v89, v89
	v_mul_f32_e32 v81, v81, v82
	v_mul_f32_e32 v73, v73, v83
	v_mul_f32_e32 v77, v77, v84
	v_mul_f32_e32 v75, v75, v85
	v_mul_f32_e32 v65, v65, v87
	v_mul_f32_e32 v79, v79, v86
	v_mul_f32_e32 v69, v69, v88
	v_mul_f32_e32 v67, v67, v89
	v_mul_f32_e32 v80, v80, v81
	v_mul_f32_e32 v72, v72, v73
	v_mul_f32_e32 v73, v76, v77
	v_mul_f32_e32 v74, v74, v75
	v_mul_f32_e32 v76, v64, v65
	v_cvt_pk_bf16_f32 v64, v80, v72
	v_cvt_pk_bf16_f32 v65, v73, v74
	v_mul_f32_e32 v75, v78, v79
	v_mul_f32_e32 v68, v68, v69
	v_mul_f32_e32 v66, v66, v67
	global_store_dwordx2 v[70:71], v[64:65], off
	v_cvt_pk_bf16_f32 v64, v75, v76
	v_cvt_pk_bf16_f32 v65, v68, v66
	global_store_dwordx2 v[70:71], v[64:65], off offset:128
	s_nop 0
	v_mov_b32_e32 v65, v56
	v_mov_b32_e32 v56, v61
	v_mov_b32_e32 v61, v58
	v_mov_b32_e32 v58, v63
	v_mov_b32_e32 v63, v48
	v_mov_b32_e32 v48, v53
	v_mov_b32_e32 v53, v50
	v_mov_b32_e32 v50, v55
	v_mov_b32_e32 v64, v60
	v_mov_b32_e32 v60, v62
	v_mov_b32_e32 v62, v52
	v_mov_b32_e32 v52, v54
	v_add_u32_e32 v54, 0x80, v144
	s_nop 1
	v_mov_b32_e32 v66, v252
	v_fmamk_f32 v55, v66, 0x3a000000, v155
	v_mul_f32_e32 v66, 0x4b800000, v55
	v_cmp_gt_f32_e32 vcc, s52, v55
	s_nop 1
	v_cndmask_b32_e32 v55, v55, v66, vcc
	v_rsq_f32_e32 v66, v55
	v_mad_i64_i32 v[54:55], s[4:5], v54, s53, v[124:125]
	v_lshl_add_u64 v[54:55], v[54:55], 0, v[116:117]
	v_mul_f32_e32 v67, 0x45800000, v66
	v_cndmask_b32_e32 v66, v66, v67, vcc
	v_pk_mul_f32 v[64:65], v[64:65], v[66:67] op_sel_hi:[1,0]
	v_pk_mul_f32 v[56:57], v[56:57], v[66:67] op_sel_hi:[1,0]
	v_pk_mul_f32 v[60:61], v[60:61], v[66:67] op_sel_hi:[1,0]
	v_pk_mul_f32 v[58:59], v[58:59], v[66:67] op_sel_hi:[1,0]
	v_pk_mul_f32 v[48:49], v[48:49], v[66:67] op_sel_hi:[1,0]
	v_pk_mul_f32 v[62:63], v[62:63], v[66:67] op_sel_hi:[1,0]
	v_pk_mul_f32 v[52:53], v[52:53], v[66:67] op_sel_hi:[1,0]
	v_pk_mul_f32 v[50:51], v[50:51], v[66:67] op_sel_hi:[1,0]
	v_mul_f32_e32 v66, 0xbfb8aa3b, v65
	v_mul_f32_e32 v67, 0xbfb8aa3b, v57
	v_mul_f32_e32 v68, 0xbfb8aa3b, v61
	v_mul_f32_e32 v69, 0xbfb8aa3b, v59
	v_mul_f32_e32 v71, 0xbfb8aa3b, v49
	v_mul_f32_e32 v70, 0xbfb8aa3b, v63
	v_mul_f32_e32 v72, 0xbfb8aa3b, v53
	v_mul_f32_e32 v73, 0xbfb8aa3b, v51
	v_exp_f32_e32 v66, v66
	v_exp_f32_e32 v67, v67
	v_exp_f32_e32 v68, v68
	v_exp_f32_e32 v69, v69
	v_exp_f32_e32 v71, v71
	v_exp_f32_e32 v70, v70
	v_exp_f32_e32 v72, v72
	v_exp_f32_e32 v73, v73
	v_add_f32_e32 v66, 1.0, v66
	v_add_f32_e32 v67, 1.0, v67
	v_add_f32_e32 v68, 1.0, v68
	v_add_f32_e32 v69, 1.0, v69
	v_add_f32_e32 v71, 1.0, v71
	v_add_f32_e32 v70, 1.0, v70
	v_add_f32_e32 v72, 1.0, v72
	v_add_f32_e32 v73, 1.0, v73
	v_rcp_f32_e32 v66, v66
	v_rcp_f32_e32 v67, v67
	v_rcp_f32_e32 v68, v68
	v_rcp_f32_e32 v69, v69
	v_rcp_f32_e32 v71, v71
	v_rcp_f32_e32 v70, v70
	v_rcp_f32_e32 v72, v72
	v_rcp_f32_e32 v73, v73
	v_mul_f32_e32 v65, v65, v66
	v_mul_f32_e32 v57, v57, v67
	v_mul_f32_e32 v61, v61, v68
	v_mul_f32_e32 v59, v59, v69
	v_mul_f32_e32 v49, v49, v71
	v_mul_f32_e32 v63, v63, v70
	v_mul_f32_e32 v53, v53, v72
	v_mul_f32_e32 v51, v51, v73
	v_mul_f32_e32 v64, v64, v65
	v_mul_f32_e32 v56, v56, v57
	v_mul_f32_e32 v57, v60, v61
	v_mul_f32_e32 v58, v58, v59
	v_mul_f32_e32 v60, v48, v49
	v_cvt_pk_bf16_f32 v48, v64, v56
	v_cvt_pk_bf16_f32 v49, v57, v58
	v_mul_f32_e32 v59, v62, v63
	v_mul_f32_e32 v52, v52, v53
	v_mul_f32_e32 v50, v50, v51
	global_store_dwordx2 v[54:55], v[48:49], off
	v_cvt_pk_bf16_f32 v48, v59, v60
	v_cvt_pk_bf16_f32 v49, v52, v50
	global_store_dwordx2 v[54:55], v[48:49], off offset:128
	s_nop 0
	v_mov_b32_e32 v49, v40
	v_mov_b32_e32 v40, v45
	v_mov_b32_e32 v45, v42
	v_mov_b32_e32 v42, v47
	v_mov_b32_e32 v47, v32
	v_mov_b32_e32 v32, v37
	v_mov_b32_e32 v37, v34
	v_mov_b32_e32 v34, v39
	v_mov_b32_e32 v48, v44
	v_mov_b32_e32 v44, v46
	v_mov_b32_e32 v46, v36
	v_mov_b32_e32 v36, v38
	v_add_u32_e32 v38, 0x90, v144
	s_nop 1
	v_mov_b32_e32 v50, v253
	v_fmamk_f32 v39, v50, 0x3a000000, v155
	v_mul_f32_e32 v50, 0x4b800000, v39
	v_cmp_gt_f32_e32 vcc, s52, v39
	s_nop 1
	v_cndmask_b32_e32 v39, v39, v50, vcc
	v_rsq_f32_e32 v50, v39
	v_mad_i64_i32 v[38:39], s[4:5], v38, s53, v[124:125]
	v_lshl_add_u64 v[38:39], v[38:39], 0, v[116:117]
	v_mul_f32_e32 v51, 0x45800000, v50
	v_cndmask_b32_e32 v50, v50, v51, vcc
	v_pk_mul_f32 v[48:49], v[48:49], v[50:51] op_sel_hi:[1,0]
	v_pk_mul_f32 v[40:41], v[40:41], v[50:51] op_sel_hi:[1,0]
	v_pk_mul_f32 v[44:45], v[44:45], v[50:51] op_sel_hi:[1,0]
	v_pk_mul_f32 v[42:43], v[42:43], v[50:51] op_sel_hi:[1,0]
	v_pk_mul_f32 v[32:33], v[32:33], v[50:51] op_sel_hi:[1,0]
	v_pk_mul_f32 v[46:47], v[46:47], v[50:51] op_sel_hi:[1,0]
	v_pk_mul_f32 v[36:37], v[36:37], v[50:51] op_sel_hi:[1,0]
	v_pk_mul_f32 v[34:35], v[34:35], v[50:51] op_sel_hi:[1,0]
	v_mul_f32_e32 v50, 0xbfb8aa3b, v49
	v_mul_f32_e32 v51, 0xbfb8aa3b, v41
	v_mul_f32_e32 v52, 0xbfb8aa3b, v45
	v_mul_f32_e32 v53, 0xbfb8aa3b, v43
	v_mul_f32_e32 v55, 0xbfb8aa3b, v33
	v_mul_f32_e32 v54, 0xbfb8aa3b, v47
	v_mul_f32_e32 v56, 0xbfb8aa3b, v37
	v_mul_f32_e32 v57, 0xbfb8aa3b, v35
	v_exp_f32_e32 v50, v50
	v_exp_f32_e32 v51, v51
	v_exp_f32_e32 v52, v52
; __device__ __forceinline__ unsigned cvt_pk_bf16(float lo, float hi) { unsigned r; asm volatile("v_cvt_pk_bf16_f32 %0, %1, %2" : "=v"(r) : "v"(lo), "v"(hi)); return r; }
; #define PG8_BAR __builtin_amdgcn_s_barrier()
;     __device__ __forceinline__ void operator()(const f32x4 (&acc)[2][2][4][2], const Unit& u, int wr, int wc, int fr, int fq) const {
;         const int row0 = u.pm * BM + wr * 64 + fr; const int fcol0 = u.pn * 128 + wc * 16 + 4 * fq;
; #pragma unroll
;         for (int ai = 0; ai < 2; ++ai)
; #pragma unroll
;             for (int m = 0; m < 4; ++m) {
;                 const int row = row0 + ai * HALF + m * 16; const float rs = rsqrtf(sumsq[row] * inv_n + eps);
; #pragma unroll
;                 for (int bj = 0; bj < 2; ++bj) {
;                     const f32x4 g = acc[ai][bj][m][0] * rs, up = acc[ai][bj][m][1] * rs; f32x4 a;
; #pragma unroll
;                     for (int e = 0; e < 4; ++e) a[e] = g[e] * __builtin_amdgcn_rcpf(1.f + __builtin_amdgcn_exp2f(-1.4426950408889634f * g[e])) * up[e];
;                     u32x2 w; w.x = cvt_pk_bf16(a[0], a[1]); w.y = cvt_pk_bf16(a[2], a[3]);
;                     *(u32x2*)(O + (size_t)row * ldo + fcol0 + bj * 64) = w;
;                 }
; template <class Epi, class Sched, bool ALIGN_EPI = false, bool SP2 = false>
; __device__ __forceinline__ void gemm_phase(PG8_LAS unsigned char* lds, const Gemm g, const Sched& S, const Epi& E) {
;     ...
;         if constexpr (ALIGN_EPI) { if (wr == 0) PG8_BAR; }
;         if constexpr (!Epi::AFTER_DRAIN) { E(acc, cur, wr, wc, fr, fq); S.done(cur); }
;         if (!has_next) break;
; #pragma unroll
;         for (int a = 0; a < 2; ++a)
; #pragma unroll
;             for (int b = 0; b < 2; ++b)
; #pragma unroll
;                 for (int m = 0; m < 4; ++m)
; #pragma unroll
;                     for (int n = 0; n < 2; ++n) acc[a][b][m][n] = (f32x4){0.f, 0.f, 0.f, 0.f};
;         cur = nxt; cA = nA; cB = nB; ++ui;
;         if constexpr (ALIGN_EPI) { if (wr == 1) PG8_BAR; }
	v_exp_f32_e32 v53, v53
	v_exp_f32_e32 v55, v55
	v_exp_f32_e32 v54, v54
	v_exp_f32_e32 v56, v56
	v_exp_f32_e32 v57, v57
	v_add_f32_e32 v50, 1.0, v50
	v_add_f32_e32 v51, 1.0, v51
	v_add_f32_e32 v52, 1.0, v52
	v_add_f32_e32 v53, 1.0, v53
	v_add_f32_e32 v55, 1.0, v55
	v_add_f32_e32 v54, 1.0, v54
	v_add_f32_e32 v56, 1.0, v56
	v_add_f32_e32 v57, 1.0, v57
	v_rcp_f32_e32 v50, v50
	v_rcp_f32_e32 v51, v51
	v_rcp_f32_e32 v52, v52
	v_rcp_f32_e32 v53, v53
	v_rcp_f32_e32 v55, v55
	v_rcp_f32_e32 v54, v54
	v_rcp_f32_e32 v56, v56
	v_rcp_f32_e32 v57, v57
	v_mul_f32_e32 v49, v49, v50
	v_mul_f32_e32 v41, v41, v51
	v_mul_f32_e32 v45, v45, v52
	v_mul_f32_e32 v43, v43, v53
	v_mul_f32_e32 v33, v33, v55
	v_mul_f32_e32 v47, v47, v54
	v_mul_f32_e32 v37, v37, v56
	v_mul_f32_e32 v35, v35, v57
	v_mul_f32_e32 v48, v48, v49
	v_mul_f32_e32 v40, v40, v41
	v_mul_f32_e32 v41, v44, v45
	v_mul_f32_e32 v42, v42, v43
	v_mul_f32_e32 v44, v32, v33
	v_cvt_pk_bf16_f32 v32, v48, v40
	v_cvt_pk_bf16_f32 v33, v41, v42
	v_mul_f32_e32 v43, v46, v47
	v_mul_f32_e32 v36, v36, v37
	v_mul_f32_e32 v34, v34, v35
	global_store_dwordx2 v[38:39], v[32:33], off
	v_cvt_pk_bf16_f32 v32, v43, v44
	v_cvt_pk_bf16_f32 v33, v36, v34
	global_store_dwordx2 v[38:39], v[32:33], off offset:128
	s_nop 0
	v_mov_b32_e32 v33, v24
	v_mov_b32_e32 v24, v29
	v_mov_b32_e32 v29, v26
	v_mov_b32_e32 v26, v31
	v_mov_b32_e32 v31, v16
	v_mov_b32_e32 v16, v21
	v_mov_b32_e32 v21, v18
	v_mov_b32_e32 v18, v23
	v_mov_b32_e32 v32, v28
	v_mov_b32_e32 v28, v30
	v_mov_b32_e32 v30, v20
	v_mov_b32_e32 v20, v22
	v_add_u32_e32 v22, 0xa0, v144
	s_nop 1
	v_mov_b32_e32 v34, v254
	v_fmamk_f32 v23, v34, 0x3a000000, v155
	v_mul_f32_e32 v34, 0x4b800000, v23
	v_cmp_gt_f32_e32 vcc, s52, v23
	s_nop 1
	v_cndmask_b32_e32 v23, v23, v34, vcc
	v_rsq_f32_e32 v34, v23
	v_mad_i64_i32 v[22:23], s[4:5], v22, s53, v[124:125]
	v_lshl_add_u64 v[22:23], v[22:23], 0, v[116:117]
	v_mul_f32_e32 v35, 0x45800000, v34
	v_cndmask_b32_e32 v34, v34, v35, vcc
	v_pk_mul_f32 v[32:33], v[32:33], v[34:35] op_sel_hi:[1,0]
	v_pk_mul_f32 v[24:25], v[24:25], v[34:35] op_sel_hi:[1,0]
	v_pk_mul_f32 v[28:29], v[28:29], v[34:35] op_sel_hi:[1,0]
	v_pk_mul_f32 v[26:27], v[26:27], v[34:35] op_sel_hi:[1,0]
	v_pk_mul_f32 v[16:17], v[16:17], v[34:35] op_sel_hi:[1,0]
	v_pk_mul_f32 v[30:31], v[30:31], v[34:35] op_sel_hi:[1,0]
	v_pk_mul_f32 v[20:21], v[20:21], v[34:35] op_sel_hi:[1,0]
	v_pk_mul_f32 v[18:19], v[18:19], v[34:35] op_sel_hi:[1,0]
	v_mul_f32_e32 v34, 0xbfb8aa3b, v33
	v_mul_f32_e32 v35, 0xbfb8aa3b, v25
	v_mul_f32_e32 v36, 0xbfb8aa3b, v29
	v_mul_f32_e32 v37, 0xbfb8aa3b, v27
	v_mul_f32_e32 v39, 0xbfb8aa3b, v17
	v_mul_f32_e32 v38, 0xbfb8aa3b, v31
	v_mul_f32_e32 v40, 0xbfb8aa3b, v21
	v_mul_f32_e32 v41, 0xbfb8aa3b, v19
	v_exp_f32_e32 v34, v34
	v_exp_f32_e32 v35, v35
	v_exp_f32_e32 v36, v36
	v_exp_f32_e32 v37, v37
	v_exp_f32_e32 v39, v39
	v_exp_f32_e32 v38, v38
	v_exp_f32_e32 v40, v40
	v_exp_f32_e32 v41, v41
	v_add_f32_e32 v34, 1.0, v34
	v_add_f32_e32 v35, 1.0, v35
	v_add_f32_e32 v36, 1.0, v36
	v_add_f32_e32 v37, 1.0, v37
	v_add_f32_e32 v39, 1.0, v39
	v_add_f32_e32 v38, 1.0, v38
	v_add_f32_e32 v40, 1.0, v40
	v_add_f32_e32 v41, 1.0, v41
	v_rcp_f32_e32 v34, v34
	v_rcp_f32_e32 v35, v35
	v_rcp_f32_e32 v36, v36
	v_rcp_f32_e32 v37, v37
	v_rcp_f32_e32 v39, v39
	v_rcp_f32_e32 v38, v38
	v_rcp_f32_e32 v40, v40
	v_rcp_f32_e32 v41, v41
	v_mul_f32_e32 v33, v33, v34
	v_mul_f32_e32 v25, v25, v35
	v_mul_f32_e32 v29, v29, v36
	v_mul_f32_e32 v27, v27, v37
	v_mul_f32_e32 v17, v17, v39
	v_mul_f32_e32 v31, v31, v38
	v_mul_f32_e32 v21, v21, v40
	v_mul_f32_e32 v19, v19, v41
	v_mul_f32_e32 v32, v32, v33
	v_mul_f32_e32 v24, v24, v25
	v_mul_f32_e32 v25, v28, v29
	v_mul_f32_e32 v26, v26, v27
	v_mul_f32_e32 v28, v16, v17
	v_cvt_pk_bf16_f32 v16, v32, v24
	v_cvt_pk_bf16_f32 v17, v25, v26
	v_mul_f32_e32 v27, v30, v31
	v_mul_f32_e32 v20, v20, v21
	v_mul_f32_e32 v18, v18, v19
	global_store_dwordx2 v[22:23], v[16:17], off
	v_cvt_pk_bf16_f32 v16, v27, v28
	v_cvt_pk_bf16_f32 v17, v20, v18
	global_store_dwordx2 v[22:23], v[16:17], off offset:128
	s_nop 0
	v_mov_b32_e32 v17, v8
	v_mov_b32_e32 v8, v13
	v_mov_b32_e32 v13, v10
	v_mov_b32_e32 v10, v15
	v_mov_b32_e32 v15, v0
	v_mov_b32_e32 v0, v5
	v_mov_b32_e32 v5, v2
	v_mov_b32_e32 v2, v7
	v_mov_b32_e32 v16, v12
	v_mov_b32_e32 v12, v14
	v_mov_b32_e32 v14, v4
	v_mov_b32_e32 v4, v6
	v_add_u32_e32 v6, 0xb0, v144
	s_andn2_b64 vcc, exec, s[6:7]
	s_nop 1
	v_mov_b32_e32 v18, v255
	v_fmamk_f32 v7, v18, 0x3a000000, v155
	v_mul_f32_e32 v18, 0x4b800000, v7
	v_cmp_gt_f32_e64 s[8:9], s52, v7
	s_nop 1
	v_cndmask_b32_e64 v7, v7, v18, s[8:9]
	v_rsq_f32_e32 v18, v7
	v_mad_i64_i32 v[6:7], s[4:5], v6, s53, v[124:125]
	v_lshl_add_u64 v[6:7], v[6:7], 0, v[116:117]
	v_mul_f32_e32 v19, 0x45800000, v18
	v_cndmask_b32_e64 v18, v18, v19, s[8:9]
	v_pk_mul_f32 v[16:17], v[16:17], v[18:19] op_sel_hi:[1,0]
	v_pk_mul_f32 v[8:9], v[8:9], v[18:19] op_sel_hi:[1,0]
	v_pk_mul_f32 v[12:13], v[12:13], v[18:19] op_sel_hi:[1,0]
	v_pk_mul_f32 v[10:11], v[10:11], v[18:19] op_sel_hi:[1,0]
	v_pk_mul_f32 v[0:1], v[0:1], v[18:19] op_sel_hi:[1,0]
	v_pk_mul_f32 v[14:15], v[14:15], v[18:19] op_sel_hi:[1,0]
	v_pk_mul_f32 v[4:5], v[4:5], v[18:19] op_sel_hi:[1,0]
	v_pk_mul_f32 v[2:3], v[2:3], v[18:19] op_sel_hi:[1,0]
	v_mul_f32_e32 v18, 0xbfb8aa3b, v17
	v_mul_f32_e32 v19, 0xbfb8aa3b, v9
	v_mul_f32_e32 v20, 0xbfb8aa3b, v13
	v_mul_f32_e32 v21, 0xbfb8aa3b, v11
	v_mul_f32_e32 v23, 0xbfb8aa3b, v1
	v_mul_f32_e32 v22, 0xbfb8aa3b, v15
	v_mul_f32_e32 v24, 0xbfb8aa3b, v5
	v_mul_f32_e32 v25, 0xbfb8aa3b, v3
	v_exp_f32_e32 v18, v18
	v_exp_f32_e32 v19, v19
	v_exp_f32_e32 v20, v20
	v_exp_f32_e32 v21, v21
	v_exp_f32_e32 v23, v23
	v_exp_f32_e32 v22, v22
	v_exp_f32_e32 v24, v24
	v_exp_f32_e32 v25, v25
	v_add_f32_e32 v18, 1.0, v18
	v_add_f32_e32 v19, 1.0, v19
	v_add_f32_e32 v20, 1.0, v20
	v_add_f32_e32 v21, 1.0, v21
	v_add_f32_e32 v23, 1.0, v23
	v_add_f32_e32 v22, 1.0, v22
	v_add_f32_e32 v24, 1.0, v24
	v_add_f32_e32 v25, 1.0, v25
	v_rcp_f32_e32 v18, v18
	v_rcp_f32_e32 v19, v19
	v_rcp_f32_e32 v20, v20
	v_rcp_f32_e32 v21, v21
	v_rcp_f32_e32 v23, v23
	v_rcp_f32_e32 v22, v22
	v_rcp_f32_e32 v24, v24
	v_rcp_f32_e32 v25, v25
	v_mul_f32_e32 v17, v17, v18
	v_mul_f32_e32 v9, v9, v19
	v_mul_f32_e32 v13, v13, v20
	v_mul_f32_e32 v11, v11, v21
	v_mul_f32_e32 v1, v1, v23
	v_mul_f32_e32 v15, v15, v22
	v_mul_f32_e32 v5, v5, v24
	v_mul_f32_e32 v3, v3, v25
	v_mul_f32_e32 v16, v16, v17
	v_mul_f32_e32 v8, v8, v9
	v_mul_f32_e32 v9, v12, v13
	v_mul_f32_e32 v10, v10, v11
	v_mul_f32_e32 v12, v0, v1
	v_cvt_pk_bf16_f32 v0, v16, v8
	v_cvt_pk_bf16_f32 v1, v9, v10
	s_mov_b64 s[4:5], -1
	v_mul_f32_e32 v11, v14, v15
	v_mul_f32_e32 v4, v4, v5
	v_mul_f32_e32 v2, v2, v3
	global_store_dwordx2 v[6:7], v[0:1], off
	v_cvt_pk_bf16_f32 v0, v11, v12
	v_cvt_pk_bf16_f32 v1, v4, v2
	global_store_dwordx2 v[6:7], v[0:1], off offset:128
	s_cbranch_vccnz .LBB0_346
	s_andn2_b64 vcc, exec, s[20:21]
	s_cbranch_vccnz .LBB0_345
	s_barrier
	s_branch .LBB0_345

; __device__ __forceinline__ unsigned cvt_pk_bf16(float lo, float hi) { unsigned r; asm volatile("v_cvt_pk_bf16_f32 %0, %1, %2" : "=v"(r) : "v"(lo), "v"(hi)); return r; }
;     __device__ __forceinline__ void operator()(const f32x4 (&acc)[2][2][4][2], const Unit& u, int wr, int wc, int fr, int fq) const {
;         const int row0 = u.pm * BM + wr * 64 + fr; const int t = u.pn >> 3; const float cs = t == 0 ? qscale : 1.f; bf16_t* base = O + (size_t)t * split_stride;
;         const int col0 = (u.pn & 7) * BM + wc * 32 + 8 * fq;
; #pragma unroll
;         for (int ai = 0; ai < 2; ++ai)
; #pragma unroll
;             for (int m = 0; m < 4; ++m) {
;                 const int row = row0 + ai * HALF + m * 16; const float rs = rsqrtf(sumsq[row] * inv_n + eps) * cs;
; #pragma unroll
;                 for (int bj = 0; bj < 2; ++bj) {
;                     const f32x4 v0 = acc[ai][bj][m][0] * rs, v1 = acc[ai][bj][m][1] * rs;
;                     u32x4 w; w.x = cvt_pk_bf16(v0[0], v0[1]); w.y = cvt_pk_bf16(v0[2], v0[3]); w.z = cvt_pk_bf16(v1[0], v1[1]); w.w = cvt_pk_bf16(v1[2], v1[3]);
;                     *(u32x4*)(base + (size_t)row * LDH + col0 + bj * HALF) = w;
;                 }
;             }
.LBB0_539:
	v_lshl_add_u32 v150, s10, 8, v153
	v_ashrrev_i32_e32 v151, 31, v150
	v_lshl_add_u64 v[146:147], v[150:151], 2, s[6:7]
	global_load_dword v136, v[146:147], off
	global_load_dword v249, v[146:147], off offset:64
	global_load_dword v250, v[146:147], off offset:128
	global_load_dword v251, v[146:147], off offset:192
	global_load_dword v252, v[146:147], off offset:512
	global_load_dword v253, v[146:147], off offset:576
	global_load_dword v254, v[146:147], off offset:640
	global_load_dword v255, v[146:147], off offset:704
	s_ashr_i32 s4, s11, 3
	s_cmp_lt_u32 s11, 8
	s_cselect_b64 vcc, -1, 0
	s_mul_hi_i32 s5, s4, 0xc100000
	s_mul_i32 s4, s4, 0xc100000
	v_cndmask_b32_e32 v161, 1.0, v160, vcc
	s_add_u32 s4, s0, s4
	s_addc_u32 s5, s1, s5
	s_lshl_b32 s10, s11, 8
	s_and_b32 s10, s10, 0x700
	v_lshlrev_b64 v[148:149], 12, v[150:151]
	v_or_b32_e32 v151, s10, v155
	v_or_b32_e32 v162, 16, v150
	v_ashrrev_i32_e32 v163, 31, v162
	v_lshl_add_u64 v[164:165], v[162:163], 2, s[6:7]
	s_waitcnt vmcnt(0)
	v_fmamk_f32 v136, v136, 0x3a000000, v159
	v_mul_f32_e32 v166, 0x4b800000, v136
	v_cmp_gt_f32_e32 vcc, s61, v136
	s_nop 1
	v_cndmask_b32_e32 v136, v136, v166, vcc
	v_rsq_f32_e32 v168, v136
	v_lshlrev_b32_e32 v136, 1, v151
	v_lshl_add_u64 v[166:167], s[4:5], 0, v[136:137]
	v_lshl_add_u64 v[148:149], v[166:167], 0, v[148:149]
	v_mul_f32_e32 v136, 0x45800000, v168
	v_cndmask_b32_e32 v136, v168, v136, vcc
	v_mul_f32_e32 v136, v161, v136
	v_pk_mul_f32 v[126:127], v[126:127], v[136:137] op_sel_hi:[1,0]
	v_pk_mul_f32 v[124:125], v[124:125], v[136:137] op_sel_hi:[1,0]
	v_pk_mul_f32 v[122:123], v[122:123], v[136:137] op_sel_hi:[1,0]
	v_pk_mul_f32 v[120:121], v[120:121], v[136:137] op_sel_hi:[1,0]
	v_pk_mul_f32 v[168:169], v[114:115], v[136:137] op_sel_hi:[1,0]
	v_pk_mul_f32 v[170:171], v[112:113], v[136:137] op_sel_hi:[1,0]
	v_cvt_pk_bf16_f32 v112, v124, v125
	v_cvt_pk_bf16_f32 v113, v126, v127
	v_cvt_pk_bf16_f32 v114, v120, v121
	v_cvt_pk_bf16_f32 v115, v122, v123
	v_pk_mul_f32 v[118:119], v[118:119], v[136:137] op_sel_hi:[1,0]
	v_pk_mul_f32 v[116:117], v[116:117], v[136:137] op_sel_hi:[1,0]
	global_store_dwordx4 v[148:149], v[112:115], off
	s_mov_b64 s[4:5], -1
	s_nop 0
	v_cvt_pk_bf16_f32 v112, v116, v117
	v_cvt_pk_bf16_f32 v113, v118, v119
	v_cvt_pk_bf16_f32 v114, v170, v171
	v_cvt_pk_bf16_f32 v115, v168, v169
	global_store_dwordx4 v[148:149], v[112:115], off offset:256
	s_nop 0
	s_nop 0
	v_or_b32_e32 v112, 32, v150
	v_ashrrev_i32_e32 v113, 31, v112
	v_lshl_add_u64 v[116:117], v[112:113], 2, s[6:7]
	s_nop 1
	v_mov_b32_e32 v114, v249
	v_fmamk_f32 v114, v114, 0x3a000000, v159
	v_mul_f32_e32 v115, 0x4b800000, v114
	v_cmp_gt_f32_e32 vcc, s61, v114
	s_nop 1
	v_cndmask_b32_e32 v114, v114, v115, vcc
	v_rsq_f32_e32 v118, v114
	v_lshlrev_b64 v[114:115], 12, v[162:163]
	v_lshl_add_u64 v[114:115], v[166:167], 0, v[114:115]
	v_mul_f32_e32 v119, 0x45800000, v118
	v_cndmask_b32_e32 v118, v118, v119, vcc
	v_mul_f32_e32 v118, v161, v118
	v_pk_mul_f32 v[110:111], v[110:111], v[118:119] op_sel_hi:[1,0]
	v_pk_mul_f32 v[108:109], v[108:109], v[118:119] op_sel_hi:[1,0]
	v_pk_mul_f32 v[106:107], v[106:107], v[118:119] op_sel_hi:[1,0]
	v_pk_mul_f32 v[104:105], v[104:105], v[118:119] op_sel_hi:[1,0]
	v_pk_mul_f32 v[102:103], v[102:103], v[118:119] op_sel_hi:[1,0]
	v_pk_mul_f32 v[100:101], v[100:101], v[118:119] op_sel_hi:[1,0]
	v_pk_mul_f32 v[120:121], v[98:99], v[118:119] op_sel_hi:[1,0]
	v_pk_mul_f32 v[118:119], v[96:97], v[118:119] op_sel_hi:[1,0]
	v_cvt_pk_bf16_f32 v96, v108, v109
	v_cvt_pk_bf16_f32 v97, v110, v111
	v_cvt_pk_bf16_f32 v98, v104, v105
	v_cvt_pk_bf16_f32 v99, v106, v107
	global_store_dwordx4 v[114:115], v[96:99], off
	s_nop 1
	v_cvt_pk_bf16_f32 v96, v100, v101
	v_cvt_pk_bf16_f32 v97, v102, v103
	v_cvt_pk_bf16_f32 v98, v118, v119
	v_cvt_pk_bf16_f32 v99, v120, v121
	global_store_dwordx4 v[114:115], v[96:99], off offset:256
	s_nop 0
	s_nop 0
	v_or_b32_e32 v96, 48, v150
	v_ashrrev_i32_e32 v97, 31, v96
	v_lshl_add_u64 v[100:101], v[96:97], 2, s[6:7]
	s_nop 1
	v_mov_b32_e32 v98, v250
	v_fmamk_f32 v98, v98, 0x3a000000, v159
	v_mul_f32_e32 v99, 0x4b800000, v98
	v_cmp_gt_f32_e32 vcc, s61, v98
	s_nop 1
	v_cndmask_b32_e32 v98, v98, v99, vcc
	v_rsq_f32_e32 v102, v98
	v_lshlrev_b64 v[98:99], 12, v[112:113]
	v_lshl_add_u64 v[98:99], v[166:167], 0, v[98:99]
	v_mul_f32_e32 v103, 0x45800000, v102
	v_cndmask_b32_e32 v102, v102, v103, vcc
	v_mul_f32_e32 v102, v161, v102
	v_pk_mul_f32 v[94:95], v[94:95], v[102:103] op_sel_hi:[1,0]
	v_pk_mul_f32 v[92:93], v[92:93], v[102:103] op_sel_hi:[1,0]
	v_pk_mul_f32 v[90:91], v[90:91], v[102:103] op_sel_hi:[1,0]
	v_pk_mul_f32 v[88:89], v[88:89], v[102:103] op_sel_hi:[1,0]
	v_pk_mul_f32 v[86:87], v[86:87], v[102:103] op_sel_hi:[1,0]
	v_pk_mul_f32 v[84:85], v[84:85], v[102:103] op_sel_hi:[1,0]
	v_pk_mul_f32 v[104:105], v[82:83], v[102:103] op_sel_hi:[1,0]
	v_pk_mul_f32 v[102:103], v[80:81], v[102:103] op_sel_hi:[1,0]
	v_cvt_pk_bf16_f32 v80, v92, v93
	v_cvt_pk_bf16_f32 v81, v94, v95
	v_cvt_pk_bf16_f32 v82, v88, v89
	v_cvt_pk_bf16_f32 v83, v90, v91
	global_store_dwordx4 v[98:99], v[80:83], off
	s_nop 1
	v_cvt_pk_bf16_f32 v80, v84, v85
	v_cvt_pk_bf16_f32 v81, v86, v87
	v_cvt_pk_bf16_f32 v82, v102, v103
	v_cvt_pk_bf16_f32 v83, v104, v105
	global_store_dwordx4 v[98:99], v[80:83], off offset:256
	s_nop 0
	s_nop 1
	v_mov_b32_e32 v80, v251
	v_fmamk_f32 v80, v80, 0x3a000000, v159
	v_mul_f32_e32 v81, 0x4b800000, v80
	v_cmp_gt_f32_e32 vcc, s61, v80
	s_nop 1
	v_cndmask_b32_e32 v80, v80, v81, vcc
	v_rsq_f32_e32 v82, v80
	v_lshlrev_b64 v[80:81], 12, v[96:97]
	v_lshl_add_u64 v[80:81], v[166:167], 0, v[80:81]
	v_mul_f32_e32 v83, 0x45800000, v82
; __device__ __forceinline__ unsigned cvt_pk_bf16(float lo, float hi) { unsigned r; asm volatile("v_cvt_pk_bf16_f32 %0, %1, %2" : "=v"(r) : "v"(lo), "v"(hi)); return r; }
; #define PG8_BAR __builtin_amdgcn_s_barrier()
;     __device__ __forceinline__ void operator()(const f32x4 (&acc)[2][2][4][2], const Unit& u, int wr, int wc, int fr, int fq) const {
;     ...
;                 const int row = row0 + ai * HALF + m * 16; const float rs = rsqrtf(sumsq[row] * inv_n + eps) * cs;
; #pragma unroll
;                 for (int bj = 0; bj < 2; ++bj) {
;                     const f32x4 v0 = acc[ai][bj][m][0] * rs, v1 = acc[ai][bj][m][1] * rs;
;                     u32x4 w; w.x = cvt_pk_bf16(v0[0], v0[1]); w.y = cvt_pk_bf16(v0[2], v0[3]); w.z = cvt_pk_bf16(v1[0], v1[1]); w.w = cvt_pk_bf16(v1[2], v1[3]);
;                     *(u32x4*)(base + (size_t)row * LDH + col0 + bj * HALF) = w;
;                 }
;             }
; template <class Epi, class Sched, bool ALIGN_EPI = false, bool SP2 = false>
; __device__ __forceinline__ void gemm_phase(PG8_LAS unsigned char* lds, const Gemm g, const Sched& S, const Epi& E) {
;     ...
;         if constexpr (ALIGN_EPI) { if (wr == 0) PG8_BAR; }
;         if constexpr (!Epi::AFTER_DRAIN) { E(acc, cur, wr, wc, fr, fq); S.done(cur); }
;         if (!has_next) break;
; #pragma unroll
;         for (int a = 0; a < 2; ++a)
; #pragma unroll
;             for (int b = 0; b < 2; ++b)
; #pragma unroll
;                 for (int m = 0; m < 4; ++m)
; #pragma unroll
;                     for (int n = 0; n < 2; ++n) acc[a][b][m][n] = (f32x4){0.f, 0.f, 0.f, 0.f};
;         cur = nxt; cA = nA; cB = nB; ++ui;
;         if constexpr (ALIGN_EPI) { if (wr == 1) PG8_BAR; }
	v_cndmask_b32_e32 v82, v82, v83, vcc
	v_mul_f32_e32 v82, v161, v82
	v_pk_mul_f32 v[78:79], v[78:79], v[82:83] op_sel_hi:[1,0]
	v_pk_mul_f32 v[76:77], v[76:77], v[82:83] op_sel_hi:[1,0]
	v_pk_mul_f32 v[74:75], v[74:75], v[82:83] op_sel_hi:[1,0]
	v_pk_mul_f32 v[72:73], v[72:73], v[82:83] op_sel_hi:[1,0]
	v_pk_mul_f32 v[70:71], v[70:71], v[82:83] op_sel_hi:[1,0]
	v_pk_mul_f32 v[68:69], v[68:69], v[82:83] op_sel_hi:[1,0]
	v_pk_mul_f32 v[84:85], v[66:67], v[82:83] op_sel_hi:[1,0]
	v_pk_mul_f32 v[82:83], v[64:65], v[82:83] op_sel_hi:[1,0]
	v_cvt_pk_bf16_f32 v64, v76, v77
	v_cvt_pk_bf16_f32 v65, v78, v79
	v_cvt_pk_bf16_f32 v66, v72, v73
	v_cvt_pk_bf16_f32 v67, v74, v75
	global_store_dwordx4 v[80:81], v[64:67], off
	s_nop 1
	v_cvt_pk_bf16_f32 v64, v68, v69
	v_cvt_pk_bf16_f32 v65, v70, v71
	v_cvt_pk_bf16_f32 v66, v82, v83
	v_cvt_pk_bf16_f32 v67, v84, v85
	global_store_dwordx4 v[80:81], v[64:67], off offset:256
	s_nop 0
	s_nop 0
	v_lshl_add_u64 v[64:65], v[148:149], 0, s[14:15]
	s_nop 1
	v_mov_b32_e32 v66, v252
	v_fmamk_f32 v66, v66, 0x3a000000, v159
	v_mul_f32_e32 v67, 0x4b800000, v66
	v_cmp_gt_f32_e32 vcc, s61, v66
	s_nop 1
	v_cndmask_b32_e32 v66, v66, v67, vcc
	v_rsq_f32_e32 v68, v66
	v_add_co_u32_e64 v66, s[10:11], s62, v148
	v_mul_f32_e32 v69, 0x45800000, v68
	v_cndmask_b32_e32 v68, v68, v69, vcc
	v_mul_f32_e32 v68, v161, v68
	v_addc_co_u32_e64 v67, s[10:11], 0, v149, s[10:11]
	v_pk_mul_f32 v[62:63], v[62:63], v[68:69] op_sel_hi:[1,0]
	v_pk_mul_f32 v[60:61], v[60:61], v[68:69] op_sel_hi:[1,0]
	v_pk_mul_f32 v[58:59], v[58:59], v[68:69] op_sel_hi:[1,0]
	v_pk_mul_f32 v[56:57], v[56:57], v[68:69] op_sel_hi:[1,0]
	v_pk_mul_f32 v[54:55], v[54:55], v[68:69] op_sel_hi:[1,0]
	v_pk_mul_f32 v[52:53], v[52:53], v[68:69] op_sel_hi:[1,0]
	v_pk_mul_f32 v[70:71], v[50:51], v[68:69] op_sel_hi:[1,0]
	v_pk_mul_f32 v[68:69], v[48:49], v[68:69] op_sel_hi:[1,0]
	v_cvt_pk_bf16_f32 v48, v60, v61
	v_cvt_pk_bf16_f32 v49, v62, v63
	v_cvt_pk_bf16_f32 v50, v56, v57
	v_cvt_pk_bf16_f32 v51, v58, v59
	global_store_dwordx4 v[66:67], v[48:51], off
	s_nop 1
	v_cvt_pk_bf16_f32 v48, v52, v53
	v_cvt_pk_bf16_f32 v49, v54, v55
	v_cvt_pk_bf16_f32 v50, v68, v69
	v_cvt_pk_bf16_f32 v51, v70, v71
	global_store_dwordx4 v[64:65], v[48:51], off offset:256
	s_nop 0
	s_nop 0
	v_lshl_add_u64 v[48:49], v[148:149], 0, s[36:37]
	s_nop 1
	v_mov_b32_e32 v50, v253
	v_fmamk_f32 v50, v50, 0x3a000000, v159
	v_mul_f32_e32 v51, 0x4b800000, v50
	v_cmp_gt_f32_e32 vcc, s61, v50
	s_nop 1
	v_cndmask_b32_e32 v50, v50, v51, vcc
	v_rsq_f32_e32 v52, v50
	v_add_co_u32_e64 v50, s[10:11], s63, v148
	v_mul_f32_e32 v53, 0x45800000, v52
	v_cndmask_b32_e32 v52, v52, v53, vcc
	v_mul_f32_e32 v52, v161, v52
	v_addc_co_u32_e64 v51, s[10:11], 0, v149, s[10:11]
	v_pk_mul_f32 v[46:47], v[46:47], v[52:53] op_sel_hi:[1,0]
	v_pk_mul_f32 v[44:45], v[44:45], v[52:53] op_sel_hi:[1,0]
	v_pk_mul_f32 v[42:43], v[42:43], v[52:53] op_sel_hi:[1,0]
	v_pk_mul_f32 v[40:41], v[40:41], v[52:53] op_sel_hi:[1,0]
	v_pk_mul_f32 v[38:39], v[38:39], v[52:53] op_sel_hi:[1,0]
	v_pk_mul_f32 v[36:37], v[36:37], v[52:53] op_sel_hi:[1,0]
	v_pk_mul_f32 v[54:55], v[34:35], v[52:53] op_sel_hi:[1,0]
	v_pk_mul_f32 v[52:53], v[32:33], v[52:53] op_sel_hi:[1,0]
	v_cvt_pk_bf16_f32 v32, v44, v45
	v_cvt_pk_bf16_f32 v33, v46, v47
	v_cvt_pk_bf16_f32 v34, v40, v41
	v_cvt_pk_bf16_f32 v35, v42, v43
	global_store_dwordx4 v[50:51], v[32:35], off
	s_nop 1
	v_cvt_pk_bf16_f32 v32, v36, v37
	v_cvt_pk_bf16_f32 v33, v38, v39
	v_cvt_pk_bf16_f32 v34, v52, v53
	v_cvt_pk_bf16_f32 v35, v54, v55
	global_store_dwordx4 v[48:49], v[32:35], off offset:256
	s_nop 0
	s_nop 0
	v_lshl_add_u64 v[32:33], v[148:149], 0, s[38:39]
	s_nop 1
	v_mov_b32_e32 v34, v254
	v_fmamk_f32 v34, v34, 0x3a000000, v159
	v_mul_f32_e32 v35, 0x4b800000, v34
	v_cmp_gt_f32_e32 vcc, s61, v34
	s_nop 1
	v_cndmask_b32_e32 v34, v34, v35, vcc
	v_rsq_f32_e32 v36, v34
	v_add_co_u32_e64 v34, s[10:11], s64, v148
	v_mul_f32_e32 v37, 0x45800000, v36
	v_cndmask_b32_e32 v36, v36, v37, vcc
	v_mul_f32_e32 v36, v161, v36
	v_addc_co_u32_e64 v35, s[10:11], 0, v149, s[10:11]
	v_pk_mul_f32 v[30:31], v[30:31], v[36:37] op_sel_hi:[1,0]
	v_pk_mul_f32 v[28:29], v[28:29], v[36:37] op_sel_hi:[1,0]
	v_pk_mul_f32 v[26:27], v[26:27], v[36:37] op_sel_hi:[1,0]
	v_pk_mul_f32 v[24:25], v[24:25], v[36:37] op_sel_hi:[1,0]
	v_pk_mul_f32 v[22:23], v[22:23], v[36:37] op_sel_hi:[1,0]
	v_pk_mul_f32 v[20:21], v[20:21], v[36:37] op_sel_hi:[1,0]
	v_pk_mul_f32 v[38:39], v[18:19], v[36:37] op_sel_hi:[1,0]
	v_pk_mul_f32 v[36:37], v[16:17], v[36:37] op_sel_hi:[1,0]
	v_cvt_pk_bf16_f32 v16, v28, v29
	v_cvt_pk_bf16_f32 v17, v30, v31
	v_cvt_pk_bf16_f32 v18, v24, v25
	v_cvt_pk_bf16_f32 v19, v26, v27
	global_store_dwordx4 v[34:35], v[16:19], off
	s_andn2_b64 vcc, exec, s[8:9]
	s_nop 0
	v_cvt_pk_bf16_f32 v16, v20, v21
	v_cvt_pk_bf16_f32 v17, v22, v23
	v_cvt_pk_bf16_f32 v18, v36, v37
	v_cvt_pk_bf16_f32 v19, v38, v39
	global_store_dwordx4 v[32:33], v[16:19], off offset:256
	s_nop 0
	s_nop 0
	v_lshl_add_u64 v[16:17], v[148:149], 0, s[40:41]
	s_nop 1
	v_mov_b32_e32 v18, v255
	v_fmamk_f32 v18, v18, 0x3a000000, v159
	v_mul_f32_e32 v19, 0x4b800000, v18
	v_cmp_gt_f32_e64 s[8:9], s61, v18
	s_nop 1
	v_cndmask_b32_e64 v18, v18, v19, s[8:9]
	v_rsq_f32_e32 v20, v18
	v_add_co_u32_e64 v18, s[10:11], s65, v148
	v_mul_f32_e32 v21, 0x45800000, v20
	v_cndmask_b32_e64 v20, v20, v21, s[8:9]
	v_mul_f32_e32 v20, v161, v20
	v_addc_co_u32_e64 v19, s[10:11], 0, v149, s[10:11]
	v_pk_mul_f32 v[14:15], v[14:15], v[20:21] op_sel_hi:[1,0]
	v_pk_mul_f32 v[12:13], v[12:13], v[20:21] op_sel_hi:[1,0]
	v_pk_mul_f32 v[10:11], v[10:11], v[20:21] op_sel_hi:[1,0]
	v_pk_mul_f32 v[8:9], v[8:9], v[20:21] op_sel_hi:[1,0]
	v_pk_mul_f32 v[6:7], v[6:7], v[20:21] op_sel_hi:[1,0]
	v_pk_mul_f32 v[4:5], v[4:5], v[20:21] op_sel_hi:[1,0]
	v_pk_mul_f32 v[22:23], v[2:3], v[20:21] op_sel_hi:[1,0]
	v_pk_mul_f32 v[20:21], v[0:1], v[20:21] op_sel_hi:[1,0]
	v_cvt_pk_bf16_f32 v0, v12, v13
	v_cvt_pk_bf16_f32 v1, v14, v15
	v_cvt_pk_bf16_f32 v2, v8, v9
	v_cvt_pk_bf16_f32 v3, v10, v11
	global_store_dwordx4 v[18:19], v[0:3], off
	s_nop 1
	v_cvt_pk_bf16_f32 v0, v4, v5
	v_cvt_pk_bf16_f32 v1, v6, v7
	v_cvt_pk_bf16_f32 v2, v20, v21
	v_cvt_pk_bf16_f32 v3, v22, v23
	global_store_dwordx4 v[16:17], v[0:3], off offset:256
	s_cbranch_vccnz .LBB0_532
	s_andn2_b64 vcc, exec, s[20:21]
	s_cbranch_vccnz .LBB0_531
	s_barrier
	s_branch .LBB0_531

; #define SBAR() __builtin_amdgcn_sched_barrier(0)
; #define TILE_DQ(ti) (qposf - (float)TILE_KPOS(ti))
; #define TILE_SIDE(ti) (qlo - TILE_KPOS(ti) >= 63 ? 1 : (qhi - TILE_KPOS(ti) <= 0 ? -1 : 0))
; template <int MODE>
; __device__ __forceinline__ void qkt(f32x16& p0, f32x16& p1, const bf16* Ks, const bf16x8* qr, int r32, int hi, float dq, float nsl, int side, float mi) {
;     ...
;   for (int d0 = 0; d0 < 8; ++d0) {
;     const int ko = r32 * 256 + ((((d0 & 3) * 32 + hi * 16) ^ ((r32 & 7) << 4))) + (d0 >> 2) * 128;
;     bf16x8 b0 = *reinterpret_cast<const bf16x8*>((const char*)Ks + ko);
;     bf16x8 b1 = *reinterpret_cast<const bf16x8*>((const char*)Ks + ko + 8192);
;     p0 = __builtin_amdgcn_mfma_f32_32x32x16_bf16(b0, qr[d0], p0, 0, 0, 0);
;     p1 = __builtin_amdgcn_mfma_f32_32x32x16_bf16(b1, qr[d0], p1, 0, 0, 0); }
; template <int J> ...
;     ...
;   SBAR(); qkt<0>(pB0, pB1, (bf16*)((char*)K_lds + SHM_K), qr, r32, hi, TILE_DQ(NT - 1), nsl, TILE_SIDE(NT - 1), mi);
;   finishSM(pA0, pA1, l_reg, pa0, pa1, pa2, pa3); SBAR();
;   pv_d0(o, vb0, pa0, pa1, pa2, pa3); SBAR();
.LBB0_708:
	s_movk_i32 s4, 0x70
	v_bitop3_b32 v0, v170, v222, s4 bitop3:0x78
	v_add3_u32 v173, 0, v0, v228
	ds_read_b128 v[0:3], v173 offset:49152
	ds_read_b128 v[4:7], v173 offset:57344
	s_movk_i32 s4, 0x60
	v_exp_f32_e32 v81, v81
	v_exp_f32_e32 v82, v82
	s_waitcnt lgkmcnt(1)
	v_mfma_f32_32x32x16_bf16 v[122:137], v[0:3], v[166:169], v[122:137]
	v_bitop3_b32 v0, v170, v221, 32 bitop3:0x36
	v_exp_f32_e32 v83, v83
	v_exp_f32_e32 v84, v84
	v_exp_f32_e32 v85, v85
	v_exp_f32_e32 v86, v86
	v_exp_f32_e32 v87, v87
	v_exp_f32_e32 v88, v88
	s_waitcnt lgkmcnt(0)
	v_mfma_f32_32x32x16_bf16 v[106:121], v[4:7], v[166:169], v[106:121]
	v_add3_u32 v166, 0, v0, v228
	ds_read_b128 v[0:3], v166 offset:49152
	ds_read_b128 v[4:7], v166 offset:57344
	v_exp_f32_e32 v89, v89
	s_and_b32 s3, s12, 0x3fffffc0
	s_lshl_b32 s3, s3, 2
	s_add_i32 s3, s3, 0
	s_add_i32 s3, s3, 0x10000
	s_waitcnt lgkmcnt(1)
	v_mfma_f32_32x32x16_bf16 v[122:137], v[0:3], v[162:165], v[122:137]
	v_bitop3_b32 v0, v170, v221, 64 bitop3:0x36
	s_waitcnt lgkmcnt(0)
	v_mfma_f32_32x32x16_bf16 v[106:121], v[4:7], v[162:165], v[106:121]
	v_add3_u32 v162, 0, v0, v228
	ds_read_b128 v[0:3], v162 offset:49152
	ds_read_b128 v[4:7], v162 offset:57344
	s_waitcnt lgkmcnt(1)
	v_mfma_f32_32x32x16_bf16 v[122:137], v[0:3], v[158:161], v[122:137]
	v_bitop3_b32 v0, v170, v221, s4 bitop3:0x36
	s_waitcnt lgkmcnt(0)
	v_mfma_f32_32x32x16_bf16 v[106:121], v[4:7], v[158:161], v[106:121]
	v_add3_u32 v158, 0, v0, v228
	ds_read_b128 v[0:3], v158 offset:49152
	ds_read_b128 v[4:7], v158 offset:57344
	s_waitcnt lgkmcnt(1)
	v_mfma_f32_32x32x16_bf16 v[122:137], v[0:3], v[154:157], v[122:137]
	s_waitcnt lgkmcnt(0)
	v_mfma_f32_32x32x16_bf16 v[106:121], v[4:7], v[154:157], v[106:121]
	ds_read_b128 v[0:3], v173 offset:49280
	ds_read_b128 v[4:7], v173 offset:57472
	s_waitcnt lgkmcnt(1)
	v_mfma_f32_32x32x16_bf16 v[122:137], v[0:3], v[150:153], v[122:137]
	s_waitcnt lgkmcnt(0)
	v_mfma_f32_32x32x16_bf16 v[106:121], v[4:7], v[150:153], v[106:121]
	ds_read_b128 v[0:3], v166 offset:49280
	ds_read_b128 v[4:7], v166 offset:57472
	s_waitcnt lgkmcnt(1)
	v_mfma_f32_32x32x16_bf16 v[122:137], v[0:3], v[146:149], v[122:137]
	s_waitcnt lgkmcnt(0)
	v_mfma_f32_32x32x16_bf16 v[106:121], v[4:7], v[146:149], v[106:121]
	ds_read_b128 v[0:3], v162 offset:49280
	ds_read_b128 v[4:7], v162 offset:57472
	s_waitcnt lgkmcnt(1)
	v_mfma_f32_32x32x16_bf16 v[122:137], v[0:3], v[142:145], v[122:137]
	s_waitcnt lgkmcnt(0)
	v_mfma_f32_32x32x16_bf16 v[106:121], v[4:7], v[142:145], v[106:121]
	ds_read_b128 v[0:3], v158 offset:49280
	ds_read_b128 v[4:7], v158 offset:57472
	s_waitcnt lgkmcnt(1)
	v_mfma_f32_32x32x16_bf16 v[122:137], v[0:3], v[138:141], v[122:137]
	v_exp_f32_e32 v1, v90
	v_exp_f32_e32 v3, v91
	v_exp_f32_e32 v90, v95
	v_exp_f32_e32 v91, v96
	v_add_f32_e32 v0, 0, v1
	v_add_f32_e32 v0, v3, v0
	v_exp_f32_e32 v95, v100
	s_waitcnt lgkmcnt(0)
	v_mfma_f32_32x32x16_bf16 v[106:121], v[4:7], v[138:141], v[106:121]
	v_exp_f32_e32 v5, v92
	v_exp_f32_e32 v6, v93
	v_exp_f32_e32 v7, v94
	v_exp_f32_e32 v92, v97
	v_add_f32_e32 v0, v5, v0
	v_add_f32_e32 v0, v6, v0
	v_exp_f32_e32 v93, v98
	v_add_f32_e32 v0, v7, v0
	v_exp_f32_e32 v94, v99
	v_add_f32_e32 v0, v90, v0
	v_add_f32_e32 v0, v91, v0
	v_exp_f32_e32 v96, v101
	v_add_f32_e32 v0, v92, v0
	v_exp_f32_e32 v97, v102
	v_add_f32_e32 v0, v93, v0
	v_exp_f32_e32 v98, v103
	v_add_f32_e32 v0, v94, v0
	v_exp_f32_e32 v99, v104
	v_add_f32_e32 v0, v95, v0
	v_exp_f32_e32 v100, v105
	v_add_f32_e32 v0, v96, v0
	v_exp_f32_e32 v101, v74
	v_add_f32_e32 v0, v97, v0
	v_exp_f32_e32 v102, v75
	v_add_f32_e32 v0, v98, v0
	v_exp_f32_e32 v103, v76
	v_add_f32_e32 v0, v99, v0
	v_exp_f32_e32 v104, v77
	v_add_f32_e32 v0, v100, v0
	v_exp_f32_e32 v105, v78
	v_add_f32_e32 v0, v101, v0
	v_exp_f32_e32 v138, v79
	v_add_f32_e32 v0, v102, v0
	v_exp_f32_e32 v139, v80
	v_add_f32_e32 v0, v103, v0
	v_add_f32_e32 v0, v104, v0
	v_add_f32_e32 v0, v105, v0
	v_add_f32_e32 v0, v138, v0
	v_add_f32_e32 v0, v139, v0
	v_add_f32_e32 v0, v81, v0
	v_add_f32_e32 v0, v82, v0
	v_add_f32_e32 v0, v83, v0
	v_add_f32_e32 v0, v84, v0
	v_add_f32_e32 v0, v85, v0
	v_add_f32_e32 v0, v86, v0
	v_add_f32_e32 v0, v87, v0
	v_add_f32_e32 v0, v88, v0
	v_add_f32_e32 v0, v89, v0
	v_mov_b32_e32 v2, v0
	s_nop 1
	v_permlane32_swap_b32_e32 v0, v2
	v_cvt_pk_bf16_f32 v4, v1, v3
	v_cvt_pk_bf16_f32 v5, v5, v6
	v_cvt_pk_bf16_f32 v6, v7, v90
	v_cvt_pk_bf16_f32 v7, v91, v92
	v_cvt_pk_bf16_f32 v74, v93, v94
	v_cvt_pk_bf16_f32 v75, v95, v96
	v_cvt_pk_bf16_f32 v76, v97, v98
	v_cvt_pk_bf16_f32 v77, v99, v100
	v_cvt_pk_bf16_f32 v78, v101, v102
	v_cvt_pk_bf16_f32 v79, v103, v104
	v_cvt_pk_bf16_f32 v80, v105, v138
	v_cvt_pk_bf16_f32 v81, v139, v81
	v_cvt_pk_bf16_f32 v82, v82, v83
	v_cvt_pk_bf16_f32 v83, v84, v85
	v_cvt_pk_bf16_f32 v84, v86, v87
	v_cvt_pk_bf16_f32 v85, v88, v89
	s_nop 0
	v_permlane32_swap_b32_e32 v4, v6
	v_permlane32_swap_b32_e32 v5, v7
	v_permlane32_swap_b32_e32 v74, v76
	v_permlane32_swap_b32_e32 v75, v77
	v_permlane32_swap_b32_e32 v78, v80
	v_permlane32_swap_b32_e32 v79, v81
	v_permlane32_swap_b32_e32 v82, v84
	v_permlane32_swap_b32_e32 v83, v85
	s_waitcnt lgkmcnt(0)
	ds_read_b64_tr_b16 v[86:87], v220 offset:0
	ds_read_b64_tr_b16 v[88:89], v220 offset:0x800
	ds_read_b64_tr_b16 v[90:91], v220 offset:0x1000
	ds_read_b64_tr_b16 v[92:93], v220 offset:0x1800
	ds_read_b64_tr_b16 v[94:95], v220 offset:0x2000
	ds_read_b64_tr_b16 v[96:97], v220 offset:0x2800
	ds_read_b64_tr_b16 v[98:99], v220 offset:0x3000
	ds_read_b64_tr_b16 v[100:101], v220 offset:0x3800
	s_waitcnt lgkmcnt(4)
; #define SBAR() __builtin_amdgcn_sched_barrier(0)
; template <int J> ...
;     ...
;   pv_d0(o, vb0, pa0, pa1, pa2, pa3); SBAR();
;   __syncthreads();
;   finishSM(pB0, pB1, l_reg, pa0, pa1, pa2, pa3); SBAR();
;   pv_d0(o, vb0 + (int)SHM_V, pa0, pa1, pa2, pa3);
	s_nop 0
	v_mfma_f32_32x32x16_bf16 v[58:73], v[4:7], v[86:89], v[58:73]
	ds_read_b64_tr_b16 v[86:87], v220 offset:0x200
	ds_read_b64_tr_b16 v[88:89], v220 offset:0xa00
	v_mfma_f32_32x32x16_bf16 v[58:73], v[74:77], v[90:93], v[58:73]
	ds_read_b64_tr_b16 v[90:91], v220 offset:0x1200
	ds_read_b64_tr_b16 v[92:93], v220 offset:0x1a00
	s_waitcnt lgkmcnt(4)
	v_mfma_f32_32x32x16_bf16 v[58:73], v[78:81], v[94:97], v[58:73]
	ds_read_b64_tr_b16 v[94:95], v220 offset:0x2200
	ds_read_b64_tr_b16 v[96:97], v220 offset:0x2a00
	v_mfma_f32_32x32x16_bf16 v[58:73], v[82:85], v[98:101], v[58:73]
	ds_read_b64_tr_b16 v[98:99], v220 offset:0x3200
	ds_read_b64_tr_b16 v[100:101], v220 offset:0x3a00
	s_waitcnt lgkmcnt(4)
	v_mfma_f32_32x32x16_bf16 v[42:57], v[4:7], v[86:89], v[42:57]
	ds_read_b64_tr_b16 v[86:87], v220 offset:0x400
	ds_read_b64_tr_b16 v[88:89], v220 offset:0xc00
	v_mfma_f32_32x32x16_bf16 v[42:57], v[74:77], v[90:93], v[42:57]
	ds_read_b64_tr_b16 v[90:91], v220 offset:0x1400
	ds_read_b64_tr_b16 v[92:93], v220 offset:0x1c00
	s_waitcnt lgkmcnt(4)
	v_mfma_f32_32x32x16_bf16 v[42:57], v[78:81], v[94:97], v[42:57]
	ds_read_b64_tr_b16 v[94:95], v220 offset:0x2400
	ds_read_b64_tr_b16 v[96:97], v220 offset:0x2c00
	v_mfma_f32_32x32x16_bf16 v[42:57], v[82:85], v[98:101], v[42:57]
	ds_read_b64_tr_b16 v[98:99], v220 offset:0x3400
	ds_read_b64_tr_b16 v[100:101], v220 offset:0x3c00
	s_waitcnt lgkmcnt(4)
	v_mfma_f32_32x32x16_bf16 v[26:41], v[4:7], v[86:89], v[26:41]
	ds_read_b64_tr_b16 v[86:87], v220 offset:0x600
	ds_read_b64_tr_b16 v[88:89], v220 offset:0xe00
	v_mfma_f32_32x32x16_bf16 v[26:41], v[74:77], v[90:93], v[26:41]
	ds_read_b64_tr_b16 v[90:91], v220 offset:0x1600
	ds_read_b64_tr_b16 v[92:93], v220 offset:0x1e00
	s_waitcnt lgkmcnt(4)
	v_mfma_f32_32x32x16_bf16 v[26:41], v[78:81], v[94:97], v[26:41]
	ds_read_b64_tr_b16 v[94:95], v220 offset:0x2600
	ds_read_b64_tr_b16 v[96:97], v220 offset:0x2e00
	v_mfma_f32_32x32x16_bf16 v[26:41], v[82:85], v[98:101], v[26:41]
	ds_read_b64_tr_b16 v[98:99], v220 offset:0x3600
	ds_read_b64_tr_b16 v[100:101], v220 offset:0x3e00
	s_waitcnt lgkmcnt(4)
	v_mfma_f32_32x32x16_bf16 v[10:25], v[4:7], v[86:89], v[10:25]
	s_waitcnt lgkmcnt(0)
	v_mfma_f32_32x32x16_bf16 v[10:25], v[74:77], v[90:93], v[10:25]
	v_mfma_f32_32x32x16_bf16 v[10:25], v[78:81], v[94:97], v[10:25]
	v_mfma_f32_32x32x16_bf16 v[10:25], v[82:85], v[98:101], v[10:25]
	v_exp_f32_e32 v4, v122
	v_exp_f32_e32 v5, v123
	v_exp_f32_e32 v6, v124
	v_exp_f32_e32 v7, v125
	v_exp_f32_e32 v74, v126
	v_add_f32_e32 v1, 0, v4
	v_exp_f32_e32 v75, v127
	v_add_f32_e32 v1, v5, v1
	v_exp_f32_e32 v76, v128
	v_add_f32_e32 v1, v6, v1
	v_exp_f32_e32 v77, v129
	v_add_f32_e32 v1, v7, v1
	v_exp_f32_e32 v78, v130
	v_add_f32_e32 v1, v74, v1
	v_exp_f32_e32 v79, v131
	v_add_f32_e32 v1, v75, v1
	v_exp_f32_e32 v80, v132
	v_add_f32_e32 v1, v76, v1
	v_exp_f32_e32 v81, v133
	v_add_f32_e32 v1, v77, v1
	v_exp_f32_e32 v82, v134
	v_add_f32_e32 v1, v78, v1
	v_exp_f32_e32 v83, v135
	v_add_f32_e32 v1, v79, v1
	v_exp_f32_e32 v84, v136
	v_add_f32_e32 v1, v80, v1
	v_exp_f32_e32 v85, v137
	v_add_f32_e32 v1, v81, v1
	v_exp_f32_e32 v86, v106
	v_add_f32_e32 v1, v82, v1
	v_exp_f32_e32 v87, v107
	v_add_f32_e32 v1, v83, v1
	v_exp_f32_e32 v88, v108
	v_add_f32_e32 v1, v84, v1
	v_exp_f32_e32 v89, v109
	v_add_f32_e32 v1, v85, v1
	v_exp_f32_e32 v90, v110
	v_add_f32_e32 v1, v86, v1
	v_exp_f32_e32 v91, v111
	v_add_f32_e32 v1, v87, v1
	v_exp_f32_e32 v92, v112
	v_add_f32_e32 v1, v88, v1
	v_exp_f32_e32 v93, v113
	v_add_f32_e32 v1, v89, v1
	v_exp_f32_e32 v94, v114
	v_add_f32_e32 v1, v90, v1
	v_exp_f32_e32 v95, v115
	v_add_f32_e32 v1, v91, v1
	v_exp_f32_e32 v96, v116
	v_add_f32_e32 v1, v92, v1
	v_exp_f32_e32 v97, v117
	v_add_f32_e32 v1, v93, v1
	v_exp_f32_e32 v98, v118
	v_add_f32_e32 v1, v94, v1
	v_exp_f32_e32 v99, v119
	v_add_f32_e32 v1, v95, v1
	v_exp_f32_e32 v100, v120
	v_add_f32_e32 v1, v96, v1
	v_exp_f32_e32 v101, v121
	v_add_f32_e32 v1, v97, v1
	v_add_f32_e32 v1, v98, v1
	v_add_f32_e32 v1, v99, v1
	v_add_f32_e32 v1, v100, v1
	v_add_f32_e32 v1, v101, v1
	v_mov_b32_e32 v3, v1
	s_waitcnt vmcnt(0)
	s_barrier
	s_nop 0
	v_permlane32_swap_b32_e32 v1, v3
	v_cvt_pk_bf16_f32 v4, v4, v5
	v_cvt_pk_bf16_f32 v5, v6, v7
	v_cvt_pk_bf16_f32 v6, v74, v75
	v_cvt_pk_bf16_f32 v7, v76, v77
	v_cvt_pk_bf16_f32 v74, v78, v79
	v_cvt_pk_bf16_f32 v75, v80, v81
	v_cvt_pk_bf16_f32 v76, v82, v83
	v_cvt_pk_bf16_f32 v77, v84, v85
	v_cvt_pk_bf16_f32 v78, v86, v87
	v_cvt_pk_bf16_f32 v79, v88, v89
	v_cvt_pk_bf16_f32 v80, v90, v91
	v_cvt_pk_bf16_f32 v81, v92, v93
	v_cvt_pk_bf16_f32 v82, v94, v95
	v_cvt_pk_bf16_f32 v83, v96, v97
	v_cvt_pk_bf16_f32 v84, v98, v99
	v_cvt_pk_bf16_f32 v85, v100, v101
	s_nop 0
	v_permlane32_swap_b32_e32 v4, v6
	v_permlane32_swap_b32_e32 v5, v7
	v_permlane32_swap_b32_e32 v74, v76
	v_permlane32_swap_b32_e32 v75, v77
	v_permlane32_swap_b32_e32 v78, v80
	v_permlane32_swap_b32_e32 v79, v81
	v_permlane32_swap_b32_e32 v82, v84
	v_permlane32_swap_b32_e32 v83, v85
	s_cmp_lg_u32 0, -1
	s_cselect_b32 s4, 0, 0
	s_addk_i32 s4, 0x4000
	s_waitcnt lgkmcnt(0)
	v_add_u32_e32 v102, s4, v219
	ds_read_b64_tr_b16 v[86:87], v102 offset:0
	ds_read_b64_tr_b16 v[88:89], v102 offset:0x800
	ds_read_b64_tr_b16 v[90:91], v102 offset:0x1000
	ds_read_b64_tr_b16 v[92:93], v102 offset:0x1800
	ds_read_b64_tr_b16 v[94:95], v102 offset:0x2000
	ds_read_b64_tr_b16 v[96:97], v102 offset:0x2800
	ds_read_b64_tr_b16 v[98:99], v102 offset:0x3000
	ds_read_b64_tr_b16 v[100:101], v102 offset:0x3800
	s_waitcnt lgkmcnt(4)
; #define ATT_GAS __attribute__((address_space(1)))
; __device__ __forceinline__ int crow(int r, int hi) { return (r & 3) + 8 * (r >> 2) + 4 * hi; }
; __device__ __forceinline__ float bf2f(bf16 v) { return __uint_as_float((unsigned)v << 16); }
; __device__ __forceinline__ bf16 f2bf(float f) { unsigned u = __float_as_uint(f); return (bf16)((u + 0x7fffu + ((u >> 16) & 1u)) >> 16); }
; template <int J> ...
;     ...
;   pv_d0(o, vb0 + (int)SHM_V, pa0, pa1, pa2, pa3);
;   if (hi == 0) li_l[r32] = l_reg; asm volatile("s_waitcnt lgkmcnt(0)" ::: "memory");
;   float rli[16];
; #pragma unroll
;   for (int r = 0; r < 16; ++r) rli[r] = __builtin_amdgcn_rcpf(li_l[crow(r, hi)]);
;   bf16* Ow = Ob + (long)(wid * QBLK) * LD; const float lam = (J == 0) ? *(const float*)(lds + SHM_ATTN + 4) : 0.f;
; #pragma unroll
;   for (int r = 0; r < 16; ++r) { const int orow = crow(r, hi);
;     if (wid * QBLK + orow < nvalid) {
; #pragma unroll
;       for (int d0 = 0; d0 < 4; ++d0) { ATT_GAS bf16* p = (ATT_GAS bf16*)(Ow + (long)orow * LD + d0 * 32 + r32); const float v = o[d0][r] * rli[r];
;         if (J == 1) *p = f2bf(v); else *p = f2bf(v - lam * bf2f(*p)); } } }
	s_nop 0
	v_mfma_f32_32x32x16_bf16 v[58:73], v[4:7], v[86:89], v[58:73]
	ds_read_b64_tr_b16 v[86:87], v102 offset:0x200
	ds_read_b64_tr_b16 v[88:89], v102 offset:0xa00
	v_mfma_f32_32x32x16_bf16 v[58:73], v[74:77], v[90:93], v[58:73]
	ds_read_b64_tr_b16 v[90:91], v102 offset:0x1200
	ds_read_b64_tr_b16 v[92:93], v102 offset:0x1a00
	s_waitcnt lgkmcnt(4)
	v_mfma_f32_32x32x16_bf16 v[58:73], v[78:81], v[94:97], v[58:73]
	ds_read_b64_tr_b16 v[94:95], v102 offset:0x2200
	ds_read_b64_tr_b16 v[96:97], v102 offset:0x2a00
	v_mfma_f32_32x32x16_bf16 v[58:73], v[82:85], v[98:101], v[58:73]
	ds_read_b64_tr_b16 v[98:99], v102 offset:0x3200
	ds_read_b64_tr_b16 v[100:101], v102 offset:0x3a00
	s_waitcnt lgkmcnt(4)
	v_mfma_f32_32x32x16_bf16 v[42:57], v[4:7], v[86:89], v[42:57]
	ds_read_b64_tr_b16 v[86:87], v102 offset:0x400
	ds_read_b64_tr_b16 v[88:89], v102 offset:0xc00
	v_mfma_f32_32x32x16_bf16 v[42:57], v[74:77], v[90:93], v[42:57]
	ds_read_b64_tr_b16 v[90:91], v102 offset:0x1400
	ds_read_b64_tr_b16 v[92:93], v102 offset:0x1c00
	s_waitcnt lgkmcnt(4)
	v_mfma_f32_32x32x16_bf16 v[42:57], v[78:81], v[94:97], v[42:57]
	ds_read_b64_tr_b16 v[94:95], v102 offset:0x2400
	ds_read_b64_tr_b16 v[96:97], v102 offset:0x2c00
	v_mfma_f32_32x32x16_bf16 v[42:57], v[82:85], v[98:101], v[42:57]
	ds_read_b64_tr_b16 v[98:99], v102 offset:0x3400
	ds_read_b64_tr_b16 v[100:101], v102 offset:0x3c00
	s_waitcnt lgkmcnt(4)
	v_mfma_f32_32x32x16_bf16 v[26:41], v[4:7], v[86:89], v[26:41]
	ds_read_b64_tr_b16 v[86:87], v102 offset:0x600
	ds_read_b64_tr_b16 v[88:89], v102 offset:0xe00
	v_mfma_f32_32x32x16_bf16 v[26:41], v[74:77], v[90:93], v[26:41]
	ds_read_b64_tr_b16 v[90:91], v102 offset:0x1600
	ds_read_b64_tr_b16 v[92:93], v102 offset:0x1e00
	s_waitcnt lgkmcnt(4)
	v_mfma_f32_32x32x16_bf16 v[26:41], v[78:81], v[94:97], v[26:41]
	ds_read_b64_tr_b16 v[94:95], v102 offset:0x2600
	ds_read_b64_tr_b16 v[96:97], v102 offset:0x2e00
	v_mfma_f32_32x32x16_bf16 v[26:41], v[82:85], v[98:101], v[26:41]
	ds_read_b64_tr_b16 v[98:99], v102 offset:0x3600
	ds_read_b64_tr_b16 v[100:101], v102 offset:0x3e00
	s_waitcnt lgkmcnt(4)
	v_mfma_f32_32x32x16_bf16 v[10:25], v[4:7], v[86:89], v[10:25]
	s_waitcnt lgkmcnt(0)
	v_mfma_f32_32x32x16_bf16 v[10:25], v[74:77], v[90:93], v[10:25]
	v_mfma_f32_32x32x16_bf16 v[10:25], v[78:81], v[94:97], v[10:25]
	v_cmp_gt_u32_e32 vcc, 32, v9
	v_mfma_f32_32x32x16_bf16 v[10:25], v[82:85], v[98:101], v[10:25]
	s_and_saveexec_b64 s[4:5], vcc
	v_pk_add_f32 v[0:1], v[0:1], v[2:3]
	v_lshl_add_u32 v4, v218, 2, s3
	v_add_f32_e32 v0, v227, v0
	v_add_f32_e32 v0, v0, v1
	ds_write_b32 v4, v0
	s_or_b64 exec, exec, s[4:5]
	s_ashr_i32 s23, s22, 31
	v_lshl_add_u32 v78, v216, 2, s3
	s_lshl_b64 s[4:5], s[22:23], 12
	v_readlane_b32 s3, v244, 7
	s_waitcnt lgkmcnt(0)
	s_add_u32 s4, s3, s4
	v_readlane_b32 s3, v244, 10
	ds_read2_b32 v[82:83], v78 offset0:1 offset1:2
	ds_read_b32 v9, v78 offset:12
	ds_read_b128 v[74:77], v78 offset:32
	ds_read_b128 v[4:7], v78 offset:64
	s_addc_u32 s5, s3, s5
	v_readlane_b32 s3, v244, 32
	v_lshlrev_b32_e32 v170, 1, v218
	v_or_b32_e32 v84, s22, v216
	v_mov_b32_e32 v79, s3
	ds_read_b128 v[0:3], v78 offset:96
	ds_read_b32 v79, v79
	v_lshl_add_u64 v[80:81], s[4:5], 0, v[170:171]
	v_cmp_gt_i32_e32 vcc, s8, v84
	s_and_saveexec_b64 s[4:5], vcc
	s_cbranch_execz .LBB0_712
	v_lshlrev_b32_e32 v170, 14, v217
	v_lshl_add_u64 v[84:85], v[80:81], 0, v[170:171]
	global_load_ushort v86, v[84:85], off
	global_load_ushort v249, v[84:85], off offset:64
	global_load_ushort v250, v[84:85], off offset:128
	global_load_ushort v251, v[84:85], off offset:192
	ds_read_b32 v78, v78
	s_waitcnt lgkmcnt(0)
	v_rcp_f32_e32 v78, v78
	s_waitcnt vmcnt(0)
	v_lshlrev_b32_e32 v86, 16, v86
	v_mul_f32_e32 v86, v79, v86
	v_fma_f32 v58, v58, v78, -v86
	v_bfe_u32 v86, v58, 16, 1
	v_add3_u32 v58, v58, v86, s26
	global_store_short_d16_hi v[84:85], v58, off
	v_mov_b32_e32 v58, v249
	v_lshlrev_b32_e32 v58, 16, v58
	v_mul_f32_e32 v58, v79, v58
	v_fma_f32 v42, v42, v78, -v58
	v_bfe_u32 v58, v42, 16, 1
	v_add3_u32 v42, v42, v58, s26
	global_store_short_d16_hi v[84:85], v42, off offset:64
	v_mov_b32_e32 v42, v250
	v_lshlrev_b32_e32 v42, 16, v42
	v_mul_f32_e32 v42, v79, v42
	v_fma_f32 v26, v26, v78, -v42
	v_bfe_u32 v42, v26, 16, 1
	v_add3_u32 v26, v26, v42, s26
	global_store_short_d16_hi v[84:85], v26, off offset:128
	v_mov_b32_e32 v26, v251
	v_lshlrev_b32_e32 v26, 16, v26
	v_mul_f32_e32 v26, v79, v26
	v_fma_f32 v10, v10, v78, -v26
	v_bfe_u32 v26, v10, 16, 1
	v_add3_u32 v10, v10, v26, s26
	global_store_short_d16_hi v[84:85], v10, off offset:192
.LBB0_712:
	s_or_b64 exec, exec, s[4:5]
	v_or_b32_e32 v10, 1, v216
	v_or_b32_e32 v26, s22, v10
	v_cmp_gt_i32_e32 vcc, s8, v26
	s_and_saveexec_b64 s[4:5], vcc
	s_cbranch_execz .LBB0_714
	v_lshlrev_b32_e32 v170, 12, v10
	v_lshl_add_u64 v[84:85], v[80:81], 0, v[170:171]
	global_load_ushort v10, v[84:85], off
	global_load_ushort v249, v[84:85], off offset:64
	global_load_ushort v250, v[84:85], off offset:128
	global_load_ushort v251, v[84:85], off offset:192
	s_waitcnt lgkmcnt(5)
	v_rcp_f32_e32 v26, v82
	s_waitcnt vmcnt(0)
	v_lshlrev_b32_e32 v10, 16, v10
	s_waitcnt lgkmcnt(0)
	v_mul_f32_e32 v10, v79, v10
	v_fma_f32 v10, v59, v26, -v10
	v_bfe_u32 v42, v10, 16, 1
	v_add3_u32 v10, v10, v42, s26
	global_store_short_d16_hi v[84:85], v10, off
	v_mov_b32_e32 v10, v249
	v_lshlrev_b32_e32 v10, 16, v10
	v_mul_f32_e32 v10, v79, v10
	v_fma_f32 v10, v43, v26, -v10
	v_bfe_u32 v42, v10, 16, 1
	v_add3_u32 v10, v10, v42, s26
	global_store_short_d16_hi v[84:85], v10, off offset:64
	v_mov_b32_e32 v10, v250
	v_lshlrev_b32_e32 v10, 16, v10
	v_mul_f32_e32 v10, v79, v10
	v_fma_f32 v10, v27, v26, -v10
	v_bfe_u32 v27, v10, 16, 1
	v_add3_u32 v10, v10, v27, s26
	global_store_short_d16_hi v[84:85], v10, off offset:128
	v_mov_b32_e32 v10, v251
	v_lshlrev_b32_e32 v10, 16, v10
	v_mul_f32_e32 v10, v79, v10
	v_fma_f32 v10, v11, v26, -v10
	v_bfe_u32 v11, v10, 16, 1
	v_add3_u32 v10, v10, v11, s26
	global_store_short_d16_hi v[84:85], v10, off offset:192
; #define ATT_GAS __attribute__((address_space(1)))
; __device__ __forceinline__ int crow(int r, int hi) { return (r & 3) + 8 * (r >> 2) + 4 * hi; }
; __device__ __forceinline__ float bf2f(bf16 v) { return __uint_as_float((unsigned)v << 16); }
; __device__ __forceinline__ bf16 f2bf(float f) { unsigned u = __float_as_uint(f); return (bf16)((u + 0x7fffu + ((u >> 16) & 1u)) >> 16); }
; template <int J> ...
;     ...
;   for (int r = 0; r < 16; ++r) { const int orow = crow(r, hi);
;     if (wid * QBLK + orow < nvalid) {
; #pragma unroll
;       for (int d0 = 0; d0 < 4; ++d0) { ATT_GAS bf16* p = (ATT_GAS bf16*)(Ow + (long)orow * LD + d0 * 32 + r32); const float v = o[d0][r] * rli[r];
;         if (J == 1) *p = f2bf(v); else *p = f2bf(v - lam * bf2f(*p)); } } }
.LBB0_714:
	s_or_b64 exec, exec, s[4:5]
	v_or_b32_e32 v10, 2, v216
	v_or_b32_e32 v11, s22, v10
	v_cmp_gt_i32_e32 vcc, s8, v11
	s_and_saveexec_b64 s[4:5], vcc
	s_cbranch_execz .LBB0_716
	v_lshlrev_b32_e32 v170, 12, v10
	v_lshl_add_u64 v[10:11], v[80:81], 0, v[170:171]
	global_load_ushort v27, v[10:11], off
	global_load_ushort v249, v[10:11], off offset:64
	global_load_ushort v250, v[10:11], off offset:128
	global_load_ushort v251, v[10:11], off offset:192
	s_waitcnt lgkmcnt(5)
	v_rcp_f32_e32 v26, v83
	s_waitcnt vmcnt(0)
	v_lshlrev_b32_e32 v27, 16, v27
	s_waitcnt lgkmcnt(0)
	v_mul_f32_e32 v27, v79, v27
	v_fma_f32 v27, v60, v26, -v27
	v_bfe_u32 v42, v27, 16, 1
	v_add3_u32 v27, v27, v42, s26
	global_store_short_d16_hi v[10:11], v27, off
	v_mov_b32_e32 v27, v249
	v_lshlrev_b32_e32 v27, 16, v27
	v_mul_f32_e32 v27, v79, v27
	v_fma_f32 v27, v44, v26, -v27
	v_bfe_u32 v42, v27, 16, 1
	v_add3_u32 v27, v27, v42, s26
	global_store_short_d16_hi v[10:11], v27, off offset:64
	v_mov_b32_e32 v27, v250
	v_lshlrev_b32_e32 v27, 16, v27
	v_mul_f32_e32 v27, v79, v27
	v_fma_f32 v27, v28, v26, -v27
	v_bfe_u32 v28, v27, 16, 1
	v_add3_u32 v27, v27, v28, s26
	global_store_short_d16_hi v[10:11], v27, off offset:128
	v_mov_b32_e32 v27, v251
	v_lshlrev_b32_e32 v27, 16, v27
	v_mul_f32_e32 v27, v79, v27
	v_fma_f32 v12, v12, v26, -v27
	v_bfe_u32 v26, v12, 16, 1
	v_add3_u32 v12, v12, v26, s26
	global_store_short_d16_hi v[10:11], v12, off offset:192
.LBB0_716:
	s_or_b64 exec, exec, s[4:5]
	v_or_b32_e32 v10, 3, v216
	v_or_b32_e32 v11, s22, v10
	v_cmp_gt_i32_e32 vcc, s8, v11
	s_and_saveexec_b64 s[4:5], vcc
	s_cbranch_execz .LBB0_718
	v_lshlrev_b32_e32 v170, 12, v10
	v_lshl_add_u64 v[10:11], v[80:81], 0, v[170:171]
	global_load_ushort v12, v[10:11], off
	global_load_ushort v249, v[10:11], off offset:64
	global_load_ushort v250, v[10:11], off offset:128
	global_load_ushort v251, v[10:11], off offset:192
	s_waitcnt lgkmcnt(4)
	v_rcp_f32_e32 v9, v9
	s_waitcnt vmcnt(0)
	v_lshlrev_b32_e32 v12, 16, v12
	s_waitcnt lgkmcnt(0)
	v_mul_f32_e32 v12, v79, v12
	v_fma_f32 v12, v61, v9, -v12
	v_bfe_u32 v26, v12, 16, 1
	v_add3_u32 v12, v12, v26, s26
	global_store_short_d16_hi v[10:11], v12, off
	v_mov_b32_e32 v12, v249
	v_lshlrev_b32_e32 v12, 16, v12
	v_mul_f32_e32 v12, v79, v12
	v_fma_f32 v12, v45, v9, -v12
	v_bfe_u32 v26, v12, 16, 1
	v_add3_u32 v12, v12, v26, s26
	global_store_short_d16_hi v[10:11], v12, off offset:64
	v_mov_b32_e32 v12, v250
	v_lshlrev_b32_e32 v12, 16, v12
	v_mul_f32_e32 v12, v79, v12
	v_fma_f32 v12, v29, v9, -v12
	v_bfe_u32 v26, v12, 16, 1
	v_add3_u32 v12, v12, v26, s26
	global_store_short_d16_hi v[10:11], v12, off offset:128
	v_mov_b32_e32 v12, v251
	v_lshlrev_b32_e32 v12, 16, v12
	v_mul_f32_e32 v12, v79, v12
	v_fma_f32 v9, v13, v9, -v12
	v_bfe_u32 v12, v9, 16, 1
	v_add3_u32 v9, v9, v12, s26
	global_store_short_d16_hi v[10:11], v9, off offset:192
.LBB0_718:
	s_or_b64 exec, exec, s[4:5]
	s_waitcnt lgkmcnt(4)
	v_or_b32_e32 v9, 8, v216
	v_or_b32_e32 v10, s22, v9
	v_cmp_gt_i32_e32 vcc, s8, v10
	s_and_saveexec_b64 s[4:5], vcc
	s_cbranch_execz .LBB0_720
	v_lshlrev_b32_e32 v170, 12, v9
	v_lshl_add_u64 v[10:11], v[80:81], 0, v[170:171]
	global_load_ushort v9, v[10:11], off
	global_load_ushort v249, v[10:11], off offset:64
	global_load_ushort v250, v[10:11], off offset:128
	global_load_ushort v251, v[10:11], off offset:192
	s_waitcnt lgkmcnt(3)
	v_rcp_f32_e32 v12, v74
	s_waitcnt vmcnt(0)
	v_lshlrev_b32_e32 v9, 16, v9
	s_waitcnt lgkmcnt(0)
	v_mul_f32_e32 v9, v79, v9
	v_fma_f32 v9, v62, v12, -v9
	v_bfe_u32 v13, v9, 16, 1
	v_add3_u32 v9, v9, v13, s26
	global_store_short_d16_hi v[10:11], v9, off
	v_mov_b32_e32 v9, v249
	v_lshlrev_b32_e32 v9, 16, v9
	v_mul_f32_e32 v9, v79, v9
	v_fma_f32 v9, v46, v12, -v9
	v_bfe_u32 v13, v9, 16, 1
	v_add3_u32 v9, v9, v13, s26
	global_store_short_d16_hi v[10:11], v9, off offset:64
	v_mov_b32_e32 v9, v250
	v_lshlrev_b32_e32 v9, 16, v9
	v_mul_f32_e32 v9, v79, v9
	v_fma_f32 v9, v30, v12, -v9
	v_bfe_u32 v13, v9, 16, 1
	v_add3_u32 v9, v9, v13, s26
	global_store_short_d16_hi v[10:11], v9, off offset:128
	v_mov_b32_e32 v9, v251
	v_lshlrev_b32_e32 v9, 16, v9
	v_mul_f32_e32 v9, v79, v9
	v_fma_f32 v9, v14, v12, -v9
	v_bfe_u32 v12, v9, 16, 1
	v_add3_u32 v9, v9, v12, s26
	global_store_short_d16_hi v[10:11], v9, off offset:192
.LBB0_720:
	s_or_b64 exec, exec, s[4:5]
	v_or_b32_e32 v9, 9, v216
	v_or_b32_e32 v10, s22, v9
	v_cmp_gt_i32_e32 vcc, s8, v10
	s_and_saveexec_b64 s[4:5], vcc
	s_cbranch_execz .LBB0_722
	v_lshlrev_b32_e32 v170, 12, v9
	v_lshl_add_u64 v[10:11], v[80:81], 0, v[170:171]
	global_load_ushort v9, v[10:11], off
	global_load_ushort v249, v[10:11], off offset:64
	global_load_ushort v250, v[10:11], off offset:128
	global_load_ushort v251, v[10:11], off offset:192
	s_waitcnt lgkmcnt(3)
	v_rcp_f32_e32 v12, v75
	s_waitcnt vmcnt(0)
	v_lshlrev_b32_e32 v9, 16, v9
	s_waitcnt lgkmcnt(0)
	v_mul_f32_e32 v9, v79, v9
	v_fma_f32 v9, v63, v12, -v9
	v_bfe_u32 v13, v9, 16, 1
	v_add3_u32 v9, v9, v13, s26
	global_store_short_d16_hi v[10:11], v9, off
	v_mov_b32_e32 v9, v249
	v_lshlrev_b32_e32 v9, 16, v9
	v_mul_f32_e32 v9, v79, v9
	v_fma_f32 v9, v47, v12, -v9
	v_bfe_u32 v13, v9, 16, 1
	v_add3_u32 v9, v9, v13, s26
	global_store_short_d16_hi v[10:11], v9, off offset:64
	v_mov_b32_e32 v9, v250
	v_lshlrev_b32_e32 v9, 16, v9
	v_mul_f32_e32 v9, v79, v9
	v_fma_f32 v9, v31, v12, -v9
	v_bfe_u32 v13, v9, 16, 1
	v_add3_u32 v9, v9, v13, s26
	global_store_short_d16_hi v[10:11], v9, off offset:128
	v_mov_b32_e32 v9, v251
	v_lshlrev_b32_e32 v9, 16, v9
	v_mul_f32_e32 v9, v79, v9
	v_fma_f32 v9, v15, v12, -v9
	v_bfe_u32 v12, v9, 16, 1
	v_add3_u32 v9, v9, v12, s26
	global_store_short_d16_hi v[10:11], v9, off offset:192
; #define ATT_GAS __attribute__((address_space(1)))
; __device__ __forceinline__ int crow(int r, int hi) { return (r & 3) + 8 * (r >> 2) + 4 * hi; }
; __device__ __forceinline__ float bf2f(bf16 v) { return __uint_as_float((unsigned)v << 16); }
; __device__ __forceinline__ bf16 f2bf(float f) { unsigned u = __float_as_uint(f); return (bf16)((u + 0x7fffu + ((u >> 16) & 1u)) >> 16); }
; template <int J> ...
;     ...
;   for (int r = 0; r < 16; ++r) { const int orow = crow(r, hi);
;     if (wid * QBLK + orow < nvalid) {
; #pragma unroll
;       for (int d0 = 0; d0 < 4; ++d0) { ATT_GAS bf16* p = (ATT_GAS bf16*)(Ow + (long)orow * LD + d0 * 32 + r32); const float v = o[d0][r] * rli[r];
;         if (J == 1) *p = f2bf(v); else *p = f2bf(v - lam * bf2f(*p)); } } }
.LBB0_722:
	s_or_b64 exec, exec, s[4:5]
	v_or_b32_e32 v9, 10, v216
	v_or_b32_e32 v10, s22, v9
	v_cmp_gt_i32_e32 vcc, s8, v10
	s_and_saveexec_b64 s[4:5], vcc
	s_cbranch_execz .LBB0_724
	v_lshlrev_b32_e32 v170, 12, v9
	v_lshl_add_u64 v[10:11], v[80:81], 0, v[170:171]
	global_load_ushort v9, v[10:11], off
	global_load_ushort v249, v[10:11], off offset:64
	global_load_ushort v250, v[10:11], off offset:128
	global_load_ushort v251, v[10:11], off offset:192
	s_waitcnt lgkmcnt(3)
	v_rcp_f32_e32 v12, v76
	s_waitcnt vmcnt(0)
	v_lshlrev_b32_e32 v9, 16, v9
	s_waitcnt lgkmcnt(0)
	v_mul_f32_e32 v9, v79, v9
	v_fma_f32 v9, v64, v12, -v9
	v_bfe_u32 v13, v9, 16, 1
	v_add3_u32 v9, v9, v13, s26
	global_store_short_d16_hi v[10:11], v9, off
	v_mov_b32_e32 v9, v249
	v_lshlrev_b32_e32 v9, 16, v9
	v_mul_f32_e32 v9, v79, v9
	v_fma_f32 v9, v48, v12, -v9
	v_bfe_u32 v13, v9, 16, 1
	v_add3_u32 v9, v9, v13, s26
	global_store_short_d16_hi v[10:11], v9, off offset:64
	v_mov_b32_e32 v9, v250
	v_lshlrev_b32_e32 v9, 16, v9
	v_mul_f32_e32 v9, v79, v9
	v_fma_f32 v9, v32, v12, -v9
	v_bfe_u32 v13, v9, 16, 1
	v_add3_u32 v9, v9, v13, s26
	global_store_short_d16_hi v[10:11], v9, off offset:128
	v_mov_b32_e32 v9, v251
	v_lshlrev_b32_e32 v9, 16, v9
	v_mul_f32_e32 v9, v79, v9
	v_fma_f32 v9, v16, v12, -v9
	v_bfe_u32 v12, v9, 16, 1
	v_add3_u32 v9, v9, v12, s26
	global_store_short_d16_hi v[10:11], v9, off offset:192
.LBB0_724:
	s_or_b64 exec, exec, s[4:5]
	v_or_b32_e32 v9, 11, v216
	v_or_b32_e32 v10, s22, v9
	v_cmp_gt_i32_e32 vcc, s8, v10
	s_and_saveexec_b64 s[4:5], vcc
	s_cbranch_execz .LBB0_726
	v_lshlrev_b32_e32 v170, 12, v9
	v_lshl_add_u64 v[10:11], v[80:81], 0, v[170:171]
	global_load_ushort v9, v[10:11], off
	global_load_ushort v249, v[10:11], off offset:64
	global_load_ushort v250, v[10:11], off offset:128
	global_load_ushort v251, v[10:11], off offset:192
	s_waitcnt lgkmcnt(3)
	v_rcp_f32_e32 v12, v77
	s_waitcnt vmcnt(0)
	v_lshlrev_b32_e32 v9, 16, v9
	s_waitcnt lgkmcnt(0)
	v_mul_f32_e32 v9, v79, v9
	v_fma_f32 v9, v65, v12, -v9
	v_bfe_u32 v13, v9, 16, 1
	v_add3_u32 v9, v9, v13, s26
	global_store_short_d16_hi v[10:11], v9, off
	v_mov_b32_e32 v9, v249
	v_lshlrev_b32_e32 v9, 16, v9
	v_mul_f32_e32 v9, v79, v9
	v_fma_f32 v9, v49, v12, -v9
	v_bfe_u32 v13, v9, 16, 1
	v_add3_u32 v9, v9, v13, s26
	global_store_short_d16_hi v[10:11], v9, off offset:64
	v_mov_b32_e32 v9, v250
	v_lshlrev_b32_e32 v9, 16, v9
	v_mul_f32_e32 v9, v79, v9
	v_fma_f32 v9, v33, v12, -v9
	v_bfe_u32 v13, v9, 16, 1
	v_add3_u32 v9, v9, v13, s26
	global_store_short_d16_hi v[10:11], v9, off offset:128
	v_mov_b32_e32 v9, v251
	v_lshlrev_b32_e32 v9, 16, v9
	v_mul_f32_e32 v9, v79, v9
	v_fma_f32 v9, v17, v12, -v9
	v_bfe_u32 v12, v9, 16, 1
	v_add3_u32 v9, v9, v12, s26
	global_store_short_d16_hi v[10:11], v9, off offset:192
.LBB0_726:
	s_or_b64 exec, exec, s[4:5]
	v_or_b32_e32 v9, 16, v216
	v_or_b32_e32 v10, s22, v9
	v_cmp_gt_i32_e32 vcc, s8, v10
	s_and_saveexec_b64 s[4:5], vcc
	s_cbranch_execz .LBB0_728
	v_lshlrev_b32_e32 v170, 12, v9
	v_lshl_add_u64 v[10:11], v[80:81], 0, v[170:171]
	global_load_ushort v9, v[10:11], off
	global_load_ushort v249, v[10:11], off offset:64
	global_load_ushort v250, v[10:11], off offset:128
	global_load_ushort v251, v[10:11], off offset:192
	s_waitcnt lgkmcnt(2)
	v_rcp_f32_e32 v4, v4
	s_waitcnt vmcnt(0)
	v_lshlrev_b32_e32 v9, 16, v9
	s_waitcnt lgkmcnt(0)
	v_mul_f32_e32 v9, v79, v9
	v_fma_f32 v9, v66, v4, -v9
	v_bfe_u32 v12, v9, 16, 1
	v_add3_u32 v9, v9, v12, s26
	global_store_short_d16_hi v[10:11], v9, off
	v_mov_b32_e32 v9, v249
	v_lshlrev_b32_e32 v9, 16, v9
	v_mul_f32_e32 v9, v79, v9
	v_fma_f32 v9, v50, v4, -v9
	v_bfe_u32 v12, v9, 16, 1
	v_add3_u32 v9, v9, v12, s26
	global_store_short_d16_hi v[10:11], v9, off offset:64
	v_mov_b32_e32 v9, v250
	v_lshlrev_b32_e32 v9, 16, v9
	v_mul_f32_e32 v9, v79, v9
	v_fma_f32 v9, v34, v4, -v9
	v_bfe_u32 v12, v9, 16, 1
	v_add3_u32 v9, v9, v12, s26
	global_store_short_d16_hi v[10:11], v9, off offset:128
	v_mov_b32_e32 v9, v251
	v_lshlrev_b32_e32 v9, 16, v9
	v_mul_f32_e32 v9, v79, v9
	v_fma_f32 v4, v18, v4, -v9
	v_bfe_u32 v9, v4, 16, 1
	v_add3_u32 v4, v4, v9, s26
	global_store_short_d16_hi v[10:11], v4, off offset:192
.LBB0_728:
	s_or_b64 exec, exec, s[4:5]
	s_waitcnt lgkmcnt(2)
	v_or_b32_e32 v4, 17, v216
	v_or_b32_e32 v9, s22, v4
	v_cmp_gt_i32_e32 vcc, s8, v9
	s_and_saveexec_b64 s[4:5], vcc
	s_cbranch_execz .LBB0_730
	v_lshlrev_b32_e32 v170, 12, v4
	v_rcp_f32_e32 v9, v5
	v_lshl_add_u64 v[4:5], v[80:81], 0, v[170:171]
	global_load_ushort v10, v[4:5], off
	global_load_ushort v249, v[4:5], off offset:64
	global_load_ushort v250, v[4:5], off offset:128
	global_load_ushort v251, v[4:5], off offset:192
	s_waitcnt vmcnt(0)
	v_lshlrev_b32_e32 v10, 16, v10
	s_waitcnt lgkmcnt(0)
	v_mul_f32_e32 v10, v79, v10
	v_fma_f32 v10, v67, v9, -v10
	v_bfe_u32 v11, v10, 16, 1
	v_add3_u32 v10, v10, v11, s26
	global_store_short_d16_hi v[4:5], v10, off
	v_mov_b32_e32 v10, v249
	v_lshlrev_b32_e32 v10, 16, v10
	v_mul_f32_e32 v10, v79, v10
	v_fma_f32 v10, v51, v9, -v10
	v_bfe_u32 v11, v10, 16, 1
	v_add3_u32 v10, v10, v11, s26
	global_store_short_d16_hi v[4:5], v10, off offset:64
	v_mov_b32_e32 v10, v250
	v_lshlrev_b32_e32 v10, 16, v10
	v_mul_f32_e32 v10, v79, v10
	v_fma_f32 v10, v35, v9, -v10
	v_bfe_u32 v11, v10, 16, 1
	v_add3_u32 v10, v10, v11, s26
	global_store_short_d16_hi v[4:5], v10, off offset:128
	v_mov_b32_e32 v10, v251
	v_lshlrev_b32_e32 v10, 16, v10
	v_mul_f32_e32 v10, v79, v10
	v_fma_f32 v9, v19, v9, -v10
	v_bfe_u32 v10, v9, 16, 1
	v_add3_u32 v9, v9, v10, s26
	global_store_short_d16_hi v[4:5], v9, off offset:192
; #define ATT_GAS __attribute__((address_space(1)))
; __device__ __forceinline__ int crow(int r, int hi) { return (r & 3) + 8 * (r >> 2) + 4 * hi; }
; __device__ __forceinline__ float bf2f(bf16 v) { return __uint_as_float((unsigned)v << 16); }
; __device__ __forceinline__ bf16 f2bf(float f) { unsigned u = __float_as_uint(f); return (bf16)((u + 0x7fffu + ((u >> 16) & 1u)) >> 16); }
; template <int J> ...
;     ...
;   for (int r = 0; r < 16; ++r) { const int orow = crow(r, hi);
;     if (wid * QBLK + orow < nvalid) {
; #pragma unroll
;       for (int d0 = 0; d0 < 4; ++d0) { ATT_GAS bf16* p = (ATT_GAS bf16*)(Ow + (long)orow * LD + d0 * 32 + r32); const float v = o[d0][r] * rli[r];
;         if (J == 1) *p = f2bf(v); else *p = f2bf(v - lam * bf2f(*p)); } } }
.LBB0_730:
	s_or_b64 exec, exec, s[4:5]
	v_or_b32_e32 v4, 18, v216
	v_or_b32_e32 v5, s22, v4
	v_cmp_gt_i32_e32 vcc, s8, v5
	s_and_saveexec_b64 s[4:5], vcc
	s_cbranch_execz .LBB0_732
	v_lshlrev_b32_e32 v170, 12, v4
	v_lshl_add_u64 v[4:5], v[80:81], 0, v[170:171]
	global_load_ushort v9, v[4:5], off
	global_load_ushort v249, v[4:5], off offset:64
	global_load_ushort v250, v[4:5], off offset:128
	global_load_ushort v251, v[4:5], off offset:192
	v_rcp_f32_e32 v6, v6
	s_waitcnt vmcnt(0)
	v_lshlrev_b32_e32 v9, 16, v9
	s_waitcnt lgkmcnt(0)
	v_mul_f32_e32 v9, v79, v9
	v_fma_f32 v9, v68, v6, -v9
	v_bfe_u32 v10, v9, 16, 1
	v_add3_u32 v9, v9, v10, s26
	global_store_short_d16_hi v[4:5], v9, off
	v_mov_b32_e32 v9, v249
	v_lshlrev_b32_e32 v9, 16, v9
	v_mul_f32_e32 v9, v79, v9
	v_fma_f32 v9, v52, v6, -v9
	v_bfe_u32 v10, v9, 16, 1
	v_add3_u32 v9, v9, v10, s26
	global_store_short_d16_hi v[4:5], v9, off offset:64
	v_mov_b32_e32 v9, v250
	v_lshlrev_b32_e32 v9, 16, v9
	v_mul_f32_e32 v9, v79, v9
	v_fma_f32 v9, v36, v6, -v9
	v_bfe_u32 v10, v9, 16, 1
	v_add3_u32 v9, v9, v10, s26
	global_store_short_d16_hi v[4:5], v9, off offset:128
	v_mov_b32_e32 v9, v251
	v_lshlrev_b32_e32 v9, 16, v9
	v_mul_f32_e32 v9, v79, v9
	v_fma_f32 v6, v20, v6, -v9
	v_bfe_u32 v9, v6, 16, 1
	v_add3_u32 v6, v6, v9, s26
	global_store_short_d16_hi v[4:5], v6, off offset:192
.LBB0_732:
	s_or_b64 exec, exec, s[4:5]
	v_or_b32_e32 v4, 19, v216
	v_or_b32_e32 v5, s22, v4
	v_cmp_gt_i32_e32 vcc, s8, v5
	s_and_saveexec_b64 s[4:5], vcc
	s_cbranch_execz .LBB0_734
	v_lshlrev_b32_e32 v170, 12, v4
	v_lshl_add_u64 v[4:5], v[80:81], 0, v[170:171]
	v_rcp_f32_e32 v6, v7
	global_load_ushort v7, v[4:5], off
	global_load_ushort v249, v[4:5], off offset:64
	global_load_ushort v250, v[4:5], off offset:128
	global_load_ushort v251, v[4:5], off offset:192
	s_waitcnt vmcnt(0)
	v_lshlrev_b32_e32 v7, 16, v7
	s_waitcnt lgkmcnt(0)
	v_mul_f32_e32 v7, v79, v7
	v_fma_f32 v7, v69, v6, -v7
	v_bfe_u32 v9, v7, 16, 1
	v_add3_u32 v7, v7, v9, s26
	global_store_short_d16_hi v[4:5], v7, off
	v_mov_b32_e32 v7, v249
	v_lshlrev_b32_e32 v7, 16, v7
	v_mul_f32_e32 v7, v79, v7
	v_fma_f32 v7, v53, v6, -v7
	v_bfe_u32 v9, v7, 16, 1
	v_add3_u32 v7, v7, v9, s26
	global_store_short_d16_hi v[4:5], v7, off offset:64
	v_mov_b32_e32 v7, v250
	v_lshlrev_b32_e32 v7, 16, v7
	v_mul_f32_e32 v7, v79, v7
	v_fma_f32 v7, v37, v6, -v7
	v_bfe_u32 v9, v7, 16, 1
	v_add3_u32 v7, v7, v9, s26
	global_store_short_d16_hi v[4:5], v7, off offset:128
	v_mov_b32_e32 v7, v251
	v_lshlrev_b32_e32 v7, 16, v7
	v_mul_f32_e32 v7, v79, v7
	v_fma_f32 v6, v21, v6, -v7
	v_bfe_u32 v7, v6, 16, 1
	v_add3_u32 v6, v6, v7, s26
	global_store_short_d16_hi v[4:5], v6, off offset:192
.LBB0_734:
	s_or_b64 exec, exec, s[4:5]
	v_or_b32_e32 v4, 24, v216
	v_or_b32_e32 v5, s22, v4
	v_cmp_gt_i32_e32 vcc, s8, v5
	s_and_saveexec_b64 s[4:5], vcc
	s_cbranch_execz .LBB0_736
	v_lshlrev_b32_e32 v170, 12, v4
	v_lshl_add_u64 v[4:5], v[80:81], 0, v[170:171]
	global_load_ushort v6, v[4:5], off
	global_load_ushort v249, v[4:5], off offset:64
	global_load_ushort v250, v[4:5], off offset:128
	global_load_ushort v251, v[4:5], off offset:192
	s_waitcnt lgkmcnt(1)
	v_rcp_f32_e32 v0, v0
	s_waitcnt vmcnt(0)
	v_lshlrev_b32_e32 v6, 16, v6
	s_waitcnt lgkmcnt(0)
	v_mul_f32_e32 v6, v79, v6
	v_fma_f32 v6, v70, v0, -v6
	v_bfe_u32 v7, v6, 16, 1
	v_add3_u32 v6, v6, v7, s26
	global_store_short_d16_hi v[4:5], v6, off
	v_mov_b32_e32 v6, v249
	v_lshlrev_b32_e32 v6, 16, v6
	v_mul_f32_e32 v6, v79, v6
	v_fma_f32 v6, v54, v0, -v6
	v_bfe_u32 v7, v6, 16, 1
	v_add3_u32 v6, v6, v7, s26
	global_store_short_d16_hi v[4:5], v6, off offset:64
	v_mov_b32_e32 v6, v250
	v_lshlrev_b32_e32 v6, 16, v6
	v_mul_f32_e32 v6, v79, v6
	v_fma_f32 v6, v38, v0, -v6
	v_bfe_u32 v7, v6, 16, 1
	v_add3_u32 v6, v6, v7, s26
	global_store_short_d16_hi v[4:5], v6, off offset:128
	v_mov_b32_e32 v6, v251
	v_lshlrev_b32_e32 v6, 16, v6
	v_mul_f32_e32 v6, v79, v6
	v_fma_f32 v0, v22, v0, -v6
	v_bfe_u32 v6, v0, 16, 1
	v_add3_u32 v0, v0, v6, s26
	global_store_short_d16_hi v[4:5], v0, off offset:192
.LBB0_736:
	s_or_b64 exec, exec, s[4:5]
	s_waitcnt lgkmcnt(1)
	v_or_b32_e32 v0, 25, v216
	v_or_b32_e32 v4, s22, v0
	v_cmp_gt_i32_e32 vcc, s8, v4
	s_and_saveexec_b64 s[4:5], vcc
	s_cbranch_execz .LBB0_738
	v_lshlrev_b32_e32 v170, 12, v0
	v_rcp_f32_e32 v4, v1
	v_lshl_add_u64 v[0:1], v[80:81], 0, v[170:171]
	global_load_ushort v5, v[0:1], off
	global_load_ushort v249, v[0:1], off offset:64
	global_load_ushort v250, v[0:1], off offset:128
	global_load_ushort v251, v[0:1], off offset:192
	s_waitcnt vmcnt(0)
	v_lshlrev_b32_e32 v5, 16, v5
	s_waitcnt lgkmcnt(0)
	v_mul_f32_e32 v5, v79, v5
	v_fma_f32 v5, v71, v4, -v5
	v_bfe_u32 v6, v5, 16, 1
	v_add3_u32 v5, v5, v6, s26
	global_store_short_d16_hi v[0:1], v5, off
	v_mov_b32_e32 v5, v249
	v_lshlrev_b32_e32 v5, 16, v5
	v_mul_f32_e32 v5, v79, v5
	v_fma_f32 v5, v55, v4, -v5
	v_bfe_u32 v6, v5, 16, 1
	v_add3_u32 v5, v5, v6, s26
	global_store_short_d16_hi v[0:1], v5, off offset:64
	v_mov_b32_e32 v5, v250
	v_lshlrev_b32_e32 v5, 16, v5
	v_mul_f32_e32 v5, v79, v5
	v_fma_f32 v5, v39, v4, -v5
	v_bfe_u32 v6, v5, 16, 1
	v_add3_u32 v5, v5, v6, s26
	global_store_short_d16_hi v[0:1], v5, off offset:128
	v_mov_b32_e32 v5, v251
	v_lshlrev_b32_e32 v5, 16, v5
	v_mul_f32_e32 v5, v79, v5
	v_fma_f32 v4, v23, v4, -v5
	v_bfe_u32 v5, v4, 16, 1
	v_add3_u32 v4, v4, v5, s26
	global_store_short_d16_hi v[0:1], v4, off offset:192
.LBB0_738:
	s_or_b64 exec, exec, s[4:5]
	v_or_b32_e32 v0, 26, v216
	v_or_b32_e32 v1, s22, v0
	v_cmp_gt_i32_e32 vcc, s8, v1
	s_and_saveexec_b64 s[4:5], vcc
	s_cbranch_execz .LBB0_740
	v_lshlrev_b32_e32 v170, 12, v0
	v_lshl_add_u64 v[0:1], v[80:81], 0, v[170:171]
	global_load_ushort v4, v[0:1], off
	global_load_ushort v249, v[0:1], off offset:64
	global_load_ushort v250, v[0:1], off offset:128
	global_load_ushort v251, v[0:1], off offset:192
	v_rcp_f32_e32 v2, v2
	s_waitcnt vmcnt(0)
	v_lshlrev_b32_e32 v4, 16, v4
	s_waitcnt lgkmcnt(0)
	v_mul_f32_e32 v4, v79, v4
	v_fma_f32 v4, v72, v2, -v4
	v_bfe_u32 v5, v4, 16, 1
	v_add3_u32 v4, v4, v5, s26
	global_store_short_d16_hi v[0:1], v4, off
	v_mov_b32_e32 v4, v249
	v_lshlrev_b32_e32 v4, 16, v4
	v_mul_f32_e32 v4, v79, v4
	v_fma_f32 v4, v56, v2, -v4
	v_bfe_u32 v5, v4, 16, 1
	v_add3_u32 v4, v4, v5, s26
	global_store_short_d16_hi v[0:1], v4, off offset:64
	v_mov_b32_e32 v4, v250
	v_lshlrev_b32_e32 v4, 16, v4
	v_mul_f32_e32 v4, v79, v4
	v_fma_f32 v4, v40, v2, -v4
	v_bfe_u32 v5, v4, 16, 1
	v_add3_u32 v4, v4, v5, s26
	global_store_short_d16_hi v[0:1], v4, off offset:128
	v_mov_b32_e32 v4, v251
	v_lshlrev_b32_e32 v4, 16, v4
	v_mul_f32_e32 v4, v79, v4
	v_fma_f32 v2, v24, v2, -v4
	v_bfe_u32 v4, v2, 16, 1
	v_add3_u32 v2, v2, v4, s26
	global_store_short_d16_hi v[0:1], v2, off offset:192

; __device__ __forceinline__ unsigned cvt_pk_bf16(float lo, float hi) { unsigned r; asm volatile("v_cvt_pk_bf16_f32 %0, %1, %2" : "=v"(r) : "v"(lo), "v"(hi)); return r; }
;     __device__ __forceinline__ void operator()(const f32x4 (&acc)[2][2][4][2], const Unit& u, int wr, int wc, int fr, int fq) const {
;         const int row0 = u.pm * BM + wr * 64 + fr; const int fcol0 = u.pn * 128 + wc * 16 + 4 * fq;
; #pragma unroll
;         for (int ai = 0; ai < 2; ++ai)
; #pragma unroll
;             for (int m = 0; m < 4; ++m) {
;                 const int row = row0 + ai * HALF + m * 16; const float rs = rsqrtf(sumsq[row] * inv_n + eps);
; #pragma unroll
;                 for (int bj = 0; bj < 2; ++bj) {
;                     const f32x4 g = acc[ai][bj][m][0] * rs, up = acc[ai][bj][m][1] * rs; f32x4 a;
; #pragma unroll
;                     for (int e = 0; e < 4; ++e) a[e] = g[e] * __builtin_amdgcn_rcpf(1.f + __builtin_amdgcn_exp2f(-1.4426950408889634f * g[e])) * up[e];
;                     u32x2 w; w.x = cvt_pk_bf16(a[0], a[1]); w.y = cvt_pk_bf16(a[2], a[3]);
;                     *(u32x2*)(O + (size_t)row * ldo + fcol0 + bj * 64) = w;
;                 }
.LBB0_1052:
	v_lshl_add_u32 v144, s8, 8, v148
	v_ashrrev_i32_e32 v145, 31, v144
	v_lshl_add_u64 v[146:147], v[144:145], 2, s[16:17]
	global_load_dword v145, v[146:147], off
	global_load_dword v249, v[146:147], off offset:64
	global_load_dword v250, v[146:147], off offset:128
	global_load_dword v251, v[146:147], off offset:192
	global_load_dword v252, v[146:147], off offset:512
	global_load_dword v253, v[146:147], off offset:576
	global_load_dword v254, v[146:147], off offset:640
	global_load_dword v255, v[146:147], off offset:704
	v_lshl_or_b32 v156, s9, 7, v150
	v_mov_b32_e32 v158, v124
	v_mov_b32_e32 v159, v120
	v_mov_b32_e32 v120, v125
	v_mov_b32_e32 v160, v126
	v_mov_b32_e32 v161, v122
	v_mov_b32_e32 v122, v127
	v_mov_b32_e32 v126, v116
	v_mov_b32_e32 v127, v112
	v_mov_b32_e32 v112, v117
	v_or_b32_e32 v164, 16, v144
	v_mov_b32_e32 v162, v118
	v_mov_b32_e32 v163, v114
	v_mov_b32_e32 v114, v119
	v_ashrrev_i32_e32 v157, 31, v156
	v_ashrrev_i32_e32 v165, 31, v164
	v_lshlrev_b64 v[116:117], 1, v[156:157]
	v_lshl_add_u64 v[156:157], v[164:165], 2, s[16:17]
	v_mov_b64_e32 v[124:125], s[10:11]
	v_mad_i64_i32 v[118:119], s[4:5], v144, s51, v[124:125]
	v_lshl_add_u64 v[118:119], v[118:119], 0, v[116:117]
	s_waitcnt vmcnt(0)
	v_fmamk_f32 v145, v145, 0x3a000000, v154
	v_mul_f32_e32 v155, 0x4b800000, v145
	v_cmp_gt_f32_e32 vcc, s50, v145
	s_nop 1
	v_cndmask_b32_e32 v145, v145, v155, vcc
	v_rsq_f32_e32 v145, v145
	s_nop 0
	v_mul_f32_e32 v155, 0x45800000, v145
	v_cndmask_b32_e32 v166, v145, v155, vcc
	v_pk_mul_f32 v[158:159], v[158:159], v[166:167] op_sel_hi:[1,0]
	v_pk_mul_f32 v[120:121], v[120:121], v[166:167] op_sel_hi:[1,0]
	v_pk_mul_f32 v[160:161], v[160:161], v[166:167] op_sel_hi:[1,0]
	v_pk_mul_f32 v[122:123], v[122:123], v[166:167] op_sel_hi:[1,0]
	v_pk_mul_f32 v[126:127], v[126:127], v[166:167] op_sel_hi:[1,0]
	v_pk_mul_f32 v[112:113], v[112:113], v[166:167] op_sel_hi:[1,0]
	v_pk_mul_f32 v[162:163], v[162:163], v[166:167] op_sel_hi:[1,0]
	v_pk_mul_f32 v[114:115], v[114:115], v[166:167] op_sel_hi:[1,0]
	v_mul_f32_e32 v145, 0xbfb8aa3b, v159
	v_mul_f32_e32 v155, 0xbfb8aa3b, v121
	v_mul_f32_e32 v165, 0xbfb8aa3b, v161
	v_mul_f32_e32 v166, 0xbfb8aa3b, v123
	v_mul_f32_e32 v167, 0xbfb8aa3b, v127
	v_mul_f32_e32 v168, 0xbfb8aa3b, v113
	v_mul_f32_e32 v169, 0xbfb8aa3b, v163
	v_mul_f32_e32 v170, 0xbfb8aa3b, v115
	v_exp_f32_e32 v145, v145
	v_exp_f32_e32 v155, v155
	v_exp_f32_e32 v165, v165
	v_exp_f32_e32 v166, v166
	v_exp_f32_e32 v167, v167
	v_exp_f32_e32 v168, v168
	v_exp_f32_e32 v169, v169
	v_exp_f32_e32 v170, v170
	v_add_f32_e32 v145, 1.0, v145
	v_add_f32_e32 v155, 1.0, v155
	v_add_f32_e32 v165, 1.0, v165
	v_add_f32_e32 v166, 1.0, v166
	v_add_f32_e32 v167, 1.0, v167
	v_add_f32_e32 v168, 1.0, v168
	v_add_f32_e32 v169, 1.0, v169
	v_add_f32_e32 v170, 1.0, v170
	v_rcp_f32_e32 v145, v145
	v_rcp_f32_e32 v155, v155
	v_rcp_f32_e32 v165, v165
	v_rcp_f32_e32 v166, v166
	v_rcp_f32_e32 v167, v167
	v_rcp_f32_e32 v168, v168
	v_rcp_f32_e32 v169, v169
	v_rcp_f32_e32 v170, v170
	v_mul_f32_e32 v145, v159, v145
	v_mul_f32_e32 v121, v121, v155
	v_mul_f32_e32 v155, v161, v165
	v_mul_f32_e32 v123, v123, v166
	v_mul_f32_e32 v127, v127, v167
	v_mul_f32_e32 v113, v113, v168
	v_mul_f32_e32 v159, v163, v169
	v_mul_f32_e32 v115, v115, v170
	v_mul_f32_e32 v145, v158, v145
	v_mul_f32_e32 v120, v120, v121
	v_mul_f32_e32 v121, v160, v155
	v_mul_f32_e32 v122, v122, v123
	v_mul_f32_e32 v123, v126, v127
	v_mul_f32_e32 v126, v112, v113
	v_cvt_pk_bf16_f32 v112, v145, v120
	v_cvt_pk_bf16_f32 v113, v121, v122
	v_mul_f32_e32 v127, v162, v159
	v_mul_f32_e32 v114, v114, v115
	global_store_dwordx2 v[118:119], v[112:113], off
	v_cvt_pk_bf16_f32 v112, v123, v126
	v_cvt_pk_bf16_f32 v113, v127, v114
	global_store_dwordx2 v[118:119], v[112:113], off offset:128
	s_nop 0
	v_mov_b32_e32 v113, v104
	v_mov_b32_e32 v104, v109
	v_mov_b32_e32 v109, v106
	v_mov_b32_e32 v106, v111
	v_mov_b32_e32 v111, v96
	v_mov_b32_e32 v96, v101
	v_mov_b32_e32 v101, v98
	v_mov_b32_e32 v98, v103
	v_mov_b32_e32 v112, v108
	v_mov_b32_e32 v108, v110
	v_mov_b32_e32 v110, v100
	v_mov_b32_e32 v100, v102
	v_or_b32_e32 v102, 32, v144
	v_mad_i64_i32 v[114:115], s[4:5], v164, s51, v[124:125]
	v_lshl_add_u64 v[114:115], v[114:115], 0, v[116:117]
	s_nop 1
	v_mov_b32_e32 v118, v249
	v_fmamk_f32 v103, v118, 0x3a000000, v154
	v_mul_f32_e32 v118, 0x4b800000, v103
	v_cmp_gt_f32_e32 vcc, s50, v103
	s_nop 1
	v_cndmask_b32_e32 v103, v103, v118, vcc
	v_rsq_f32_e32 v120, v103
	v_ashrrev_i32_e32 v103, 31, v102
	v_lshl_add_u64 v[118:119], v[102:103], 2, s[16:17]
	v_mul_f32_e32 v103, 0x45800000, v120
	v_cndmask_b32_e32 v120, v120, v103, vcc
	v_pk_mul_f32 v[112:113], v[112:113], v[120:121] op_sel_hi:[1,0]
	v_pk_mul_f32 v[104:105], v[104:105], v[120:121] op_sel_hi:[1,0]
	v_pk_mul_f32 v[108:109], v[108:109], v[120:121] op_sel_hi:[1,0]
	v_pk_mul_f32 v[106:107], v[106:107], v[120:121] op_sel_hi:[1,0]
	v_pk_mul_f32 v[96:97], v[96:97], v[120:121] op_sel_hi:[1,0]
	v_pk_mul_f32 v[110:111], v[110:111], v[120:121] op_sel_hi:[1,0]
	v_pk_mul_f32 v[100:101], v[100:101], v[120:121] op_sel_hi:[1,0]
	v_pk_mul_f32 v[98:99], v[98:99], v[120:121] op_sel_hi:[1,0]
	v_mul_f32_e32 v103, 0xbfb8aa3b, v113
	v_mul_f32_e32 v120, 0xbfb8aa3b, v105
	v_mul_f32_e32 v121, 0xbfb8aa3b, v109
	v_mul_f32_e32 v122, 0xbfb8aa3b, v107
	v_mul_f32_e32 v126, 0xbfb8aa3b, v97
	v_mul_f32_e32 v123, 0xbfb8aa3b, v111
	v_mul_f32_e32 v127, 0xbfb8aa3b, v101
	v_mul_f32_e32 v145, 0xbfb8aa3b, v99
	v_exp_f32_e32 v103, v103
	v_exp_f32_e32 v120, v120
	v_exp_f32_e32 v121, v121
	v_exp_f32_e32 v122, v122
	v_exp_f32_e32 v126, v126
	v_exp_f32_e32 v123, v123
	v_exp_f32_e32 v127, v127
	v_exp_f32_e32 v145, v145
; __device__ __forceinline__ unsigned cvt_pk_bf16(float lo, float hi) { unsigned r; asm volatile("v_cvt_pk_bf16_f32 %0, %1, %2" : "=v"(r) : "v"(lo), "v"(hi)); return r; }
;     __device__ __forceinline__ void operator()(const f32x4 (&acc)[2][2][4][2], const Unit& u, int wr, int wc, int fr, int fq) const {
;     ...
;                 const int row = row0 + ai * HALF + m * 16; const float rs = rsqrtf(sumsq[row] * inv_n + eps);
; #pragma unroll
;                 for (int bj = 0; bj < 2; ++bj) {
;                     const f32x4 g = acc[ai][bj][m][0] * rs, up = acc[ai][bj][m][1] * rs; f32x4 a;
; #pragma unroll
;                     for (int e = 0; e < 4; ++e) a[e] = g[e] * __builtin_amdgcn_rcpf(1.f + __builtin_amdgcn_exp2f(-1.4426950408889634f * g[e])) * up[e];
;                     u32x2 w; w.x = cvt_pk_bf16(a[0], a[1]); w.y = cvt_pk_bf16(a[2], a[3]);
;                     *(u32x2*)(O + (size_t)row * ldo + fcol0 + bj * 64) = w;
	v_add_f32_e32 v103, 1.0, v103
	v_add_f32_e32 v120, 1.0, v120
	v_add_f32_e32 v121, 1.0, v121
	v_add_f32_e32 v122, 1.0, v122
	v_add_f32_e32 v126, 1.0, v126
	v_add_f32_e32 v123, 1.0, v123
	v_add_f32_e32 v127, 1.0, v127
	v_add_f32_e32 v145, 1.0, v145
	v_rcp_f32_e32 v103, v103
	v_rcp_f32_e32 v120, v120
	v_rcp_f32_e32 v121, v121
	v_rcp_f32_e32 v122, v122
	v_rcp_f32_e32 v126, v126
	v_rcp_f32_e32 v123, v123
	v_rcp_f32_e32 v127, v127
	v_rcp_f32_e32 v145, v145
	v_mul_f32_e32 v103, v113, v103
	v_mul_f32_e32 v105, v105, v120
	v_mul_f32_e32 v109, v109, v121
	v_mul_f32_e32 v107, v107, v122
	v_mul_f32_e32 v97, v97, v126
	v_mul_f32_e32 v111, v111, v123
	v_mul_f32_e32 v101, v101, v127
	v_mul_f32_e32 v99, v99, v145
	v_mul_f32_e32 v103, v112, v103
	v_mul_f32_e32 v104, v104, v105
	v_mul_f32_e32 v105, v108, v109
	v_mul_f32_e32 v106, v106, v107
	v_mul_f32_e32 v108, v96, v97
	v_cvt_pk_bf16_f32 v96, v103, v104
	v_cvt_pk_bf16_f32 v97, v105, v106
	v_mul_f32_e32 v107, v110, v111
	v_mul_f32_e32 v100, v100, v101
	v_mul_f32_e32 v98, v98, v99
	global_store_dwordx2 v[114:115], v[96:97], off
	v_cvt_pk_bf16_f32 v96, v107, v108
	v_cvt_pk_bf16_f32 v97, v100, v98
	global_store_dwordx2 v[114:115], v[96:97], off offset:128
	s_nop 0
	v_mov_b32_e32 v97, v88
	v_mov_b32_e32 v88, v93
	v_mov_b32_e32 v93, v90
	v_mov_b32_e32 v90, v95
	v_mov_b32_e32 v95, v80
	v_mov_b32_e32 v80, v85
	v_mov_b32_e32 v85, v82
	v_mov_b32_e32 v82, v87
	v_mad_i64_i32 v[98:99], s[4:5], v102, s51, v[124:125]
	v_mov_b32_e32 v96, v92
	v_mov_b32_e32 v92, v94
	v_mov_b32_e32 v94, v84
	v_mov_b32_e32 v84, v86
	v_or_b32_e32 v86, 48, v144
	v_lshl_add_u64 v[98:99], v[98:99], 0, v[116:117]
	s_nop 1
	v_mov_b32_e32 v100, v250
	v_fmamk_f32 v87, v100, 0x3a000000, v154
	v_mul_f32_e32 v100, 0x4b800000, v87
	v_cmp_gt_f32_e32 vcc, s50, v87
	s_nop 1
	v_cndmask_b32_e32 v87, v87, v100, vcc
	v_rsq_f32_e32 v102, v87
	v_ashrrev_i32_e32 v87, 31, v86
	v_lshl_add_u64 v[100:101], v[86:87], 2, s[16:17]
	v_mul_f32_e32 v87, 0x45800000, v102
	v_cndmask_b32_e32 v102, v102, v87, vcc
	v_pk_mul_f32 v[96:97], v[96:97], v[102:103] op_sel_hi:[1,0]
	v_pk_mul_f32 v[88:89], v[88:89], v[102:103] op_sel_hi:[1,0]
	v_pk_mul_f32 v[92:93], v[92:93], v[102:103] op_sel_hi:[1,0]
	v_pk_mul_f32 v[90:91], v[90:91], v[102:103] op_sel_hi:[1,0]
	v_pk_mul_f32 v[80:81], v[80:81], v[102:103] op_sel_hi:[1,0]
	v_pk_mul_f32 v[94:95], v[94:95], v[102:103] op_sel_hi:[1,0]
	v_pk_mul_f32 v[84:85], v[84:85], v[102:103] op_sel_hi:[1,0]
	v_pk_mul_f32 v[82:83], v[82:83], v[102:103] op_sel_hi:[1,0]
	v_mul_f32_e32 v87, 0xbfb8aa3b, v97
	v_mul_f32_e32 v102, 0xbfb8aa3b, v89
	v_mul_f32_e32 v103, 0xbfb8aa3b, v93
	v_mul_f32_e32 v104, 0xbfb8aa3b, v91
	v_mul_f32_e32 v106, 0xbfb8aa3b, v81
	v_mul_f32_e32 v105, 0xbfb8aa3b, v95
	v_mul_f32_e32 v107, 0xbfb8aa3b, v85
	v_mul_f32_e32 v108, 0xbfb8aa3b, v83
	v_exp_f32_e32 v87, v87
	v_exp_f32_e32 v102, v102
	v_exp_f32_e32 v103, v103
	v_exp_f32_e32 v104, v104
	v_exp_f32_e32 v106, v106
	v_exp_f32_e32 v105, v105
	v_exp_f32_e32 v107, v107
	v_exp_f32_e32 v108, v108
	v_add_f32_e32 v87, 1.0, v87
	v_add_f32_e32 v102, 1.0, v102
	v_add_f32_e32 v103, 1.0, v103
	v_add_f32_e32 v104, 1.0, v104
	v_add_f32_e32 v106, 1.0, v106
	v_add_f32_e32 v105, 1.0, v105
	v_add_f32_e32 v107, 1.0, v107
	v_add_f32_e32 v108, 1.0, v108
	v_rcp_f32_e32 v87, v87
	v_rcp_f32_e32 v102, v102
	v_rcp_f32_e32 v103, v103
	v_rcp_f32_e32 v104, v104
	v_rcp_f32_e32 v106, v106
	v_rcp_f32_e32 v105, v105
	v_rcp_f32_e32 v107, v107
	v_rcp_f32_e32 v108, v108
	v_mul_f32_e32 v87, v97, v87
	v_mul_f32_e32 v89, v89, v102
	v_mul_f32_e32 v93, v93, v103
	v_mul_f32_e32 v91, v91, v104
	v_mul_f32_e32 v81, v81, v106
	v_mul_f32_e32 v95, v95, v105
	v_mul_f32_e32 v85, v85, v107
	v_mul_f32_e32 v83, v83, v108
	v_mul_f32_e32 v87, v96, v87
	v_mul_f32_e32 v88, v88, v89
	v_mul_f32_e32 v89, v92, v93
	v_mul_f32_e32 v90, v90, v91
	v_mul_f32_e32 v92, v80, v81
	v_cvt_pk_bf16_f32 v80, v87, v88
	v_cvt_pk_bf16_f32 v81, v89, v90
	v_mul_f32_e32 v91, v94, v95
	v_mul_f32_e32 v84, v84, v85
	v_mul_f32_e32 v82, v82, v83
	global_store_dwordx2 v[98:99], v[80:81], off
	v_cvt_pk_bf16_f32 v80, v91, v92
	v_cvt_pk_bf16_f32 v81, v84, v82
	global_store_dwordx2 v[98:99], v[80:81], off offset:128
	s_nop 0
	v_mov_b32_e32 v80, v76
	v_mov_b32_e32 v76, v78
	v_mov_b32_e32 v78, v68
	v_mov_b32_e32 v68, v70
	v_mov_b32_e32 v81, v72
	v_mov_b32_e32 v72, v77
	v_mov_b32_e32 v77, v74
	v_mov_b32_e32 v74, v79
	v_mov_b32_e32 v79, v64
	v_mov_b32_e32 v64, v69
	v_mov_b32_e32 v69, v66
	v_mov_b32_e32 v66, v71
	s_nop 1
	v_mov_b32_e32 v82, v251
	v_fmamk_f32 v70, v82, 0x3a000000, v154
	v_mul_f32_e32 v71, 0x4b800000, v70
	v_cmp_gt_f32_e32 vcc, s50, v70
	s_nop 1
	v_cndmask_b32_e32 v70, v70, v71, vcc
	v_rsq_f32_e32 v82, v70
	v_mad_i64_i32 v[70:71], s[4:5], v86, s51, v[124:125]
	v_lshl_add_u64 v[70:71], v[70:71], 0, v[116:117]
	v_mul_f32_e32 v83, 0x45800000, v82
	v_cndmask_b32_e32 v82, v82, v83, vcc
	v_pk_mul_f32 v[80:81], v[80:81], v[82:83] op_sel_hi:[1,0]
	v_pk_mul_f32 v[72:73], v[72:73], v[82:83] op_sel_hi:[1,0]
	v_pk_mul_f32 v[76:77], v[76:77], v[82:83] op_sel_hi:[1,0]
	v_pk_mul_f32 v[74:75], v[74:75], v[82:83] op_sel_hi:[1,0]
	v_pk_mul_f32 v[64:65], v[64:65], v[82:83] op_sel_hi:[1,0]
	v_pk_mul_f32 v[78:79], v[78:79], v[82:83] op_sel_hi:[1,0]
	v_pk_mul_f32 v[68:69], v[68:69], v[82:83] op_sel_hi:[1,0]
	v_pk_mul_f32 v[66:67], v[66:67], v[82:83] op_sel_hi:[1,0]
	v_mul_f32_e32 v82, 0xbfb8aa3b, v81
	v_mul_f32_e32 v83, 0xbfb8aa3b, v73
	v_mul_f32_e32 v84, 0xbfb8aa3b, v77
	v_mul_f32_e32 v85, 0xbfb8aa3b, v75
	v_mul_f32_e32 v87, 0xbfb8aa3b, v65
	v_mul_f32_e32 v86, 0xbfb8aa3b, v79
	v_mul_f32_e32 v88, 0xbfb8aa3b, v69
	v_mul_f32_e32 v89, 0xbfb8aa3b, v67
	v_exp_f32_e32 v82, v82
; __device__ __forceinline__ unsigned cvt_pk_bf16(float lo, float hi) { unsigned r; asm volatile("v_cvt_pk_bf16_f32 %0, %1, %2" : "=v"(r) : "v"(lo), "v"(hi)); return r; }
;     __device__ __forceinline__ void operator()(const f32x4 (&acc)[2][2][4][2], const Unit& u, int wr, int wc, int fr, int fq) const {
;     ...
;                 const int row = row0 + ai * HALF + m * 16; const float rs = rsqrtf(sumsq[row] * inv_n + eps);
; #pragma unroll
;                 for (int bj = 0; bj < 2; ++bj) {
;                     const f32x4 g = acc[ai][bj][m][0] * rs, up = acc[ai][bj][m][1] * rs; f32x4 a;
; #pragma unroll
;                     for (int e = 0; e < 4; ++e) a[e] = g[e] * __builtin_amdgcn_rcpf(1.f + __builtin_amdgcn_exp2f(-1.4426950408889634f * g[e])) * up[e];
;                     u32x2 w; w.x = cvt_pk_bf16(a[0], a[1]); w.y = cvt_pk_bf16(a[2], a[3]);
;                     *(u32x2*)(O + (size_t)row * ldo + fcol0 + bj * 64) = w;
	v_exp_f32_e32 v83, v83
	v_exp_f32_e32 v84, v84
	v_exp_f32_e32 v85, v85
	v_exp_f32_e32 v87, v87
	v_exp_f32_e32 v86, v86
	v_exp_f32_e32 v88, v88
	v_exp_f32_e32 v89, v89
	v_add_f32_e32 v82, 1.0, v82
	v_add_f32_e32 v83, 1.0, v83
	v_add_f32_e32 v84, 1.0, v84
	v_add_f32_e32 v85, 1.0, v85
	v_add_f32_e32 v87, 1.0, v87
	v_add_f32_e32 v86, 1.0, v86
	v_add_f32_e32 v88, 1.0, v88
	v_add_f32_e32 v89, 1.0, v89
	v_rcp_f32_e32 v82, v82
	v_rcp_f32_e32 v83, v83
	v_rcp_f32_e32 v84, v84
	v_rcp_f32_e32 v85, v85
	v_rcp_f32_e32 v87, v87
	v_rcp_f32_e32 v86, v86
	v_rcp_f32_e32 v88, v88
	v_rcp_f32_e32 v89, v89
	v_mul_f32_e32 v81, v81, v82
	v_mul_f32_e32 v73, v73, v83
	v_mul_f32_e32 v77, v77, v84
	v_mul_f32_e32 v75, v75, v85
	v_mul_f32_e32 v65, v65, v87
	v_mul_f32_e32 v79, v79, v86
	v_mul_f32_e32 v69, v69, v88
	v_mul_f32_e32 v67, v67, v89
	v_mul_f32_e32 v80, v80, v81
	v_mul_f32_e32 v72, v72, v73
	v_mul_f32_e32 v73, v76, v77
	v_mul_f32_e32 v74, v74, v75
	v_mul_f32_e32 v76, v64, v65
	v_cvt_pk_bf16_f32 v64, v80, v72
	v_cvt_pk_bf16_f32 v65, v73, v74
	v_mul_f32_e32 v75, v78, v79
	v_mul_f32_e32 v68, v68, v69
	v_mul_f32_e32 v66, v66, v67
	global_store_dwordx2 v[70:71], v[64:65], off
	v_cvt_pk_bf16_f32 v64, v75, v76
	v_cvt_pk_bf16_f32 v65, v68, v66
	global_store_dwordx2 v[70:71], v[64:65], off offset:128
	s_nop 0
	v_mov_b32_e32 v65, v56
	v_mov_b32_e32 v56, v61
	v_mov_b32_e32 v61, v58
	v_mov_b32_e32 v58, v63
	v_mov_b32_e32 v63, v48
	v_mov_b32_e32 v48, v53
	v_mov_b32_e32 v53, v50
	v_mov_b32_e32 v50, v55
	v_mov_b32_e32 v64, v60
	v_mov_b32_e32 v60, v62
	v_mov_b32_e32 v62, v52
	v_mov_b32_e32 v52, v54
	v_add_u32_e32 v54, 0x80, v144
	s_nop 1
	v_mov_b32_e32 v66, v252
	v_fmamk_f32 v55, v66, 0x3a000000, v154
	v_mul_f32_e32 v66, 0x4b800000, v55
	v_cmp_gt_f32_e32 vcc, s50, v55
	s_nop 1
	v_cndmask_b32_e32 v55, v55, v66, vcc
	v_rsq_f32_e32 v66, v55
	v_mad_i64_i32 v[54:55], s[4:5], v54, s51, v[124:125]
	v_lshl_add_u64 v[54:55], v[54:55], 0, v[116:117]
	v_mul_f32_e32 v67, 0x45800000, v66
	v_cndmask_b32_e32 v66, v66, v67, vcc
	v_pk_mul_f32 v[64:65], v[64:65], v[66:67] op_sel_hi:[1,0]
	v_pk_mul_f32 v[56:57], v[56:57], v[66:67] op_sel_hi:[1,0]
	v_pk_mul_f32 v[60:61], v[60:61], v[66:67] op_sel_hi:[1,0]
	v_pk_mul_f32 v[58:59], v[58:59], v[66:67] op_sel_hi:[1,0]
	v_pk_mul_f32 v[48:49], v[48:49], v[66:67] op_sel_hi:[1,0]
	v_pk_mul_f32 v[62:63], v[62:63], v[66:67] op_sel_hi:[1,0]
	v_pk_mul_f32 v[52:53], v[52:53], v[66:67] op_sel_hi:[1,0]
	v_pk_mul_f32 v[50:51], v[50:51], v[66:67] op_sel_hi:[1,0]
	v_mul_f32_e32 v66, 0xbfb8aa3b, v65
	v_mul_f32_e32 v67, 0xbfb8aa3b, v57
	v_mul_f32_e32 v68, 0xbfb8aa3b, v61
	v_mul_f32_e32 v69, 0xbfb8aa3b, v59
	v_mul_f32_e32 v71, 0xbfb8aa3b, v49
	v_mul_f32_e32 v70, 0xbfb8aa3b, v63
	v_mul_f32_e32 v72, 0xbfb8aa3b, v53
	v_mul_f32_e32 v73, 0xbfb8aa3b, v51
	v_exp_f32_e32 v66, v66
	v_exp_f32_e32 v67, v67
	v_exp_f32_e32 v68, v68
	v_exp_f32_e32 v69, v69
	v_exp_f32_e32 v71, v71
	v_exp_f32_e32 v70, v70
	v_exp_f32_e32 v72, v72
	v_exp_f32_e32 v73, v73
	v_add_f32_e32 v66, 1.0, v66
	v_add_f32_e32 v67, 1.0, v67
	v_add_f32_e32 v68, 1.0, v68
	v_add_f32_e32 v69, 1.0, v69
	v_add_f32_e32 v71, 1.0, v71
	v_add_f32_e32 v70, 1.0, v70
	v_add_f32_e32 v72, 1.0, v72
	v_add_f32_e32 v73, 1.0, v73
	v_rcp_f32_e32 v66, v66
	v_rcp_f32_e32 v67, v67
	v_rcp_f32_e32 v68, v68
	v_rcp_f32_e32 v69, v69
	v_rcp_f32_e32 v71, v71
	v_rcp_f32_e32 v70, v70
	v_rcp_f32_e32 v72, v72
	v_rcp_f32_e32 v73, v73
	v_mul_f32_e32 v65, v65, v66
	v_mul_f32_e32 v57, v57, v67
	v_mul_f32_e32 v61, v61, v68
	v_mul_f32_e32 v59, v59, v69
	v_mul_f32_e32 v49, v49, v71
	v_mul_f32_e32 v63, v63, v70
	v_mul_f32_e32 v53, v53, v72
	v_mul_f32_e32 v51, v51, v73
	v_mul_f32_e32 v64, v64, v65
	v_mul_f32_e32 v56, v56, v57
	v_mul_f32_e32 v57, v60, v61
	v_mul_f32_e32 v58, v58, v59
	v_mul_f32_e32 v60, v48, v49
	v_cvt_pk_bf16_f32 v48, v64, v56
	v_cvt_pk_bf16_f32 v49, v57, v58
	v_mul_f32_e32 v59, v62, v63
	v_mul_f32_e32 v52, v52, v53
	v_mul_f32_e32 v50, v50, v51
	global_store_dwordx2 v[54:55], v[48:49], off
	v_cvt_pk_bf16_f32 v48, v59, v60
	v_cvt_pk_bf16_f32 v49, v52, v50
	global_store_dwordx2 v[54:55], v[48:49], off offset:128
	s_nop 0
	v_mov_b32_e32 v49, v40
	v_mov_b32_e32 v40, v45
	v_mov_b32_e32 v45, v42
	v_mov_b32_e32 v42, v47
	v_mov_b32_e32 v47, v32
	v_mov_b32_e32 v32, v37
	v_mov_b32_e32 v37, v34
	v_mov_b32_e32 v34, v39
	v_mov_b32_e32 v48, v44
	v_mov_b32_e32 v44, v46
	v_mov_b32_e32 v46, v36
	v_mov_b32_e32 v36, v38
	v_add_u32_e32 v38, 0x90, v144
	s_nop 1
	v_mov_b32_e32 v50, v253
	v_fmamk_f32 v39, v50, 0x3a000000, v154
	v_mul_f32_e32 v50, 0x4b800000, v39
	v_cmp_gt_f32_e32 vcc, s50, v39
	s_nop 1
	v_cndmask_b32_e32 v39, v39, v50, vcc
	v_rsq_f32_e32 v50, v39
	v_mad_i64_i32 v[38:39], s[4:5], v38, s51, v[124:125]
	v_lshl_add_u64 v[38:39], v[38:39], 0, v[116:117]
	v_mul_f32_e32 v51, 0x45800000, v50
	v_cndmask_b32_e32 v50, v50, v51, vcc
	v_pk_mul_f32 v[48:49], v[48:49], v[50:51] op_sel_hi:[1,0]
	v_pk_mul_f32 v[40:41], v[40:41], v[50:51] op_sel_hi:[1,0]
	v_pk_mul_f32 v[44:45], v[44:45], v[50:51] op_sel_hi:[1,0]
	v_pk_mul_f32 v[42:43], v[42:43], v[50:51] op_sel_hi:[1,0]
	v_pk_mul_f32 v[32:33], v[32:33], v[50:51] op_sel_hi:[1,0]
	v_pk_mul_f32 v[46:47], v[46:47], v[50:51] op_sel_hi:[1,0]
	v_pk_mul_f32 v[36:37], v[36:37], v[50:51] op_sel_hi:[1,0]
	v_pk_mul_f32 v[34:35], v[34:35], v[50:51] op_sel_hi:[1,0]
	v_mul_f32_e32 v50, 0xbfb8aa3b, v49
	v_mul_f32_e32 v51, 0xbfb8aa3b, v41
	v_mul_f32_e32 v52, 0xbfb8aa3b, v45
	v_mul_f32_e32 v53, 0xbfb8aa3b, v43
	v_mul_f32_e32 v55, 0xbfb8aa3b, v33
	v_mul_f32_e32 v54, 0xbfb8aa3b, v47
	v_mul_f32_e32 v56, 0xbfb8aa3b, v37
	v_mul_f32_e32 v57, 0xbfb8aa3b, v35
	v_exp_f32_e32 v50, v50
	v_exp_f32_e32 v51, v51
	v_exp_f32_e32 v52, v52
; __device__ __forceinline__ unsigned cvt_pk_bf16(float lo, float hi) { unsigned r; asm volatile("v_cvt_pk_bf16_f32 %0, %1, %2" : "=v"(r) : "v"(lo), "v"(hi)); return r; }
; #define PG8_BAR __builtin_amdgcn_s_barrier()
;     __device__ __forceinline__ void operator()(const f32x4 (&acc)[2][2][4][2], const Unit& u, int wr, int wc, int fr, int fq) const {
;     ...
;                 const int row = row0 + ai * HALF + m * 16; const float rs = rsqrtf(sumsq[row] * inv_n + eps);
; #pragma unroll
;                 for (int bj = 0; bj < 2; ++bj) {
;                     const f32x4 g = acc[ai][bj][m][0] * rs, up = acc[ai][bj][m][1] * rs; f32x4 a;
; #pragma unroll
;                     for (int e = 0; e < 4; ++e) a[e] = g[e] * __builtin_amdgcn_rcpf(1.f + __builtin_amdgcn_exp2f(-1.4426950408889634f * g[e])) * up[e];
;                     u32x2 w; w.x = cvt_pk_bf16(a[0], a[1]); w.y = cvt_pk_bf16(a[2], a[3]);
;                     *(u32x2*)(O + (size_t)row * ldo + fcol0 + bj * 64) = w;
; template <class Epi, class Sched, bool ALIGN_EPI = false, bool SP2 = false>
; __device__ __forceinline__ void gemm_phase(PG8_LAS unsigned char* lds, const Gemm g, const Sched& S, const Epi& E) {
;     ...
;         if constexpr (ALIGN_EPI) { if (wr == 0) PG8_BAR; }
;         if constexpr (!Epi::AFTER_DRAIN) { E(acc, cur, wr, wc, fr, fq); S.done(cur); }
;         if (!has_next) break;
; #pragma unroll
;         for (int a = 0; a < 2; ++a)
; #pragma unroll
;             for (int b = 0; b < 2; ++b)
; #pragma unroll
;                 for (int m = 0; m < 4; ++m)
; #pragma unroll
;                     for (int n = 0; n < 2; ++n) acc[a][b][m][n] = (f32x4){0.f, 0.f, 0.f, 0.f};
;         cur = nxt; cA = nA; cB = nB; ++ui;
;         if constexpr (ALIGN_EPI) { if (wr == 1) PG8_BAR; }
	v_exp_f32_e32 v53, v53
	v_exp_f32_e32 v55, v55
	v_exp_f32_e32 v54, v54
	v_exp_f32_e32 v56, v56
	v_exp_f32_e32 v57, v57
	v_add_f32_e32 v50, 1.0, v50
	v_add_f32_e32 v51, 1.0, v51
	v_add_f32_e32 v52, 1.0, v52
	v_add_f32_e32 v53, 1.0, v53
	v_add_f32_e32 v55, 1.0, v55
	v_add_f32_e32 v54, 1.0, v54
	v_add_f32_e32 v56, 1.0, v56
	v_add_f32_e32 v57, 1.0, v57
	v_rcp_f32_e32 v50, v50
	v_rcp_f32_e32 v51, v51
	v_rcp_f32_e32 v52, v52
	v_rcp_f32_e32 v53, v53
	v_rcp_f32_e32 v55, v55
	v_rcp_f32_e32 v54, v54
	v_rcp_f32_e32 v56, v56
	v_rcp_f32_e32 v57, v57
	v_mul_f32_e32 v49, v49, v50
	v_mul_f32_e32 v41, v41, v51
	v_mul_f32_e32 v45, v45, v52
	v_mul_f32_e32 v43, v43, v53
	v_mul_f32_e32 v33, v33, v55
	v_mul_f32_e32 v47, v47, v54
	v_mul_f32_e32 v37, v37, v56
	v_mul_f32_e32 v35, v35, v57
	v_mul_f32_e32 v48, v48, v49
	v_mul_f32_e32 v40, v40, v41
	v_mul_f32_e32 v41, v44, v45
	v_mul_f32_e32 v42, v42, v43
	v_mul_f32_e32 v44, v32, v33
	v_cvt_pk_bf16_f32 v32, v48, v40
	v_cvt_pk_bf16_f32 v33, v41, v42
	v_mul_f32_e32 v43, v46, v47
	v_mul_f32_e32 v36, v36, v37
	v_mul_f32_e32 v34, v34, v35
	global_store_dwordx2 v[38:39], v[32:33], off
	v_cvt_pk_bf16_f32 v32, v43, v44
	v_cvt_pk_bf16_f32 v33, v36, v34
	global_store_dwordx2 v[38:39], v[32:33], off offset:128
	s_nop 0
	v_mov_b32_e32 v33, v24
	v_mov_b32_e32 v24, v29
	v_mov_b32_e32 v29, v26
	v_mov_b32_e32 v26, v31
	v_mov_b32_e32 v31, v16
	v_mov_b32_e32 v16, v21
	v_mov_b32_e32 v21, v18
	v_mov_b32_e32 v18, v23
	v_mov_b32_e32 v32, v28
	v_mov_b32_e32 v28, v30
	v_mov_b32_e32 v30, v20
	v_mov_b32_e32 v20, v22
	v_add_u32_e32 v22, 0xa0, v144
	s_nop 1
	v_mov_b32_e32 v34, v254
	v_fmamk_f32 v23, v34, 0x3a000000, v154
	v_mul_f32_e32 v34, 0x4b800000, v23
	v_cmp_gt_f32_e32 vcc, s50, v23
	s_nop 1
	v_cndmask_b32_e32 v23, v23, v34, vcc
	v_rsq_f32_e32 v34, v23
	v_mad_i64_i32 v[22:23], s[4:5], v22, s51, v[124:125]
	v_lshl_add_u64 v[22:23], v[22:23], 0, v[116:117]
	v_mul_f32_e32 v35, 0x45800000, v34
	v_cndmask_b32_e32 v34, v34, v35, vcc
	v_pk_mul_f32 v[32:33], v[32:33], v[34:35] op_sel_hi:[1,0]
	v_pk_mul_f32 v[24:25], v[24:25], v[34:35] op_sel_hi:[1,0]
	v_pk_mul_f32 v[28:29], v[28:29], v[34:35] op_sel_hi:[1,0]
	v_pk_mul_f32 v[26:27], v[26:27], v[34:35] op_sel_hi:[1,0]
	v_pk_mul_f32 v[16:17], v[16:17], v[34:35] op_sel_hi:[1,0]
	v_pk_mul_f32 v[30:31], v[30:31], v[34:35] op_sel_hi:[1,0]
	v_pk_mul_f32 v[20:21], v[20:21], v[34:35] op_sel_hi:[1,0]
	v_pk_mul_f32 v[18:19], v[18:19], v[34:35] op_sel_hi:[1,0]
	v_mul_f32_e32 v34, 0xbfb8aa3b, v33
	v_mul_f32_e32 v35, 0xbfb8aa3b, v25
	v_mul_f32_e32 v36, 0xbfb8aa3b, v29
	v_mul_f32_e32 v37, 0xbfb8aa3b, v27
	v_mul_f32_e32 v39, 0xbfb8aa3b, v17
	v_mul_f32_e32 v38, 0xbfb8aa3b, v31
	v_mul_f32_e32 v40, 0xbfb8aa3b, v21
	v_mul_f32_e32 v41, 0xbfb8aa3b, v19
	v_exp_f32_e32 v34, v34
	v_exp_f32_e32 v35, v35
	v_exp_f32_e32 v36, v36
	v_exp_f32_e32 v37, v37
	v_exp_f32_e32 v39, v39
	v_exp_f32_e32 v38, v38
	v_exp_f32_e32 v40, v40
	v_exp_f32_e32 v41, v41
	v_add_f32_e32 v34, 1.0, v34
	v_add_f32_e32 v35, 1.0, v35
	v_add_f32_e32 v36, 1.0, v36
	v_add_f32_e32 v37, 1.0, v37
	v_add_f32_e32 v39, 1.0, v39
	v_add_f32_e32 v38, 1.0, v38
	v_add_f32_e32 v40, 1.0, v40
	v_add_f32_e32 v41, 1.0, v41
	v_rcp_f32_e32 v34, v34
	v_rcp_f32_e32 v35, v35
	v_rcp_f32_e32 v36, v36
	v_rcp_f32_e32 v37, v37
	v_rcp_f32_e32 v39, v39
	v_rcp_f32_e32 v38, v38
	v_rcp_f32_e32 v40, v40
	v_rcp_f32_e32 v41, v41
	v_mul_f32_e32 v33, v33, v34
	v_mul_f32_e32 v25, v25, v35
	v_mul_f32_e32 v29, v29, v36
	v_mul_f32_e32 v27, v27, v37
	v_mul_f32_e32 v17, v17, v39
	v_mul_f32_e32 v31, v31, v38
	v_mul_f32_e32 v21, v21, v40
	v_mul_f32_e32 v19, v19, v41
	v_mul_f32_e32 v32, v32, v33
	v_mul_f32_e32 v24, v24, v25
	v_mul_f32_e32 v25, v28, v29
	v_mul_f32_e32 v26, v26, v27
	v_mul_f32_e32 v28, v16, v17
	v_cvt_pk_bf16_f32 v16, v32, v24
	v_cvt_pk_bf16_f32 v17, v25, v26
	v_mul_f32_e32 v27, v30, v31
	v_mul_f32_e32 v20, v20, v21
	v_mul_f32_e32 v18, v18, v19
	global_store_dwordx2 v[22:23], v[16:17], off
	v_cvt_pk_bf16_f32 v16, v27, v28
	v_cvt_pk_bf16_f32 v17, v20, v18
	global_store_dwordx2 v[22:23], v[16:17], off offset:128
	s_nop 0
	v_mov_b32_e32 v17, v8
	v_mov_b32_e32 v8, v13
	v_mov_b32_e32 v13, v10
	v_mov_b32_e32 v10, v15
	v_mov_b32_e32 v15, v0
	v_mov_b32_e32 v0, v5
	v_mov_b32_e32 v5, v2
	v_mov_b32_e32 v2, v7
	v_mov_b32_e32 v16, v12
	v_mov_b32_e32 v12, v14
	v_mov_b32_e32 v14, v4
	v_mov_b32_e32 v4, v6
	v_add_u32_e32 v6, 0xb0, v144
	s_andn2_b64 vcc, exec, s[6:7]
	s_nop 1
	v_mov_b32_e32 v18, v255
	v_fmamk_f32 v7, v18, 0x3a000000, v154
	v_mul_f32_e32 v18, 0x4b800000, v7
	v_cmp_gt_f32_e64 s[8:9], s50, v7
	s_nop 1
	v_cndmask_b32_e64 v7, v7, v18, s[8:9]
	v_rsq_f32_e32 v18, v7
	v_mad_i64_i32 v[6:7], s[4:5], v6, s51, v[124:125]
	v_lshl_add_u64 v[6:7], v[6:7], 0, v[116:117]
	v_mul_f32_e32 v19, 0x45800000, v18
	v_cndmask_b32_e64 v18, v18, v19, s[8:9]
	v_pk_mul_f32 v[16:17], v[16:17], v[18:19] op_sel_hi:[1,0]
	v_pk_mul_f32 v[8:9], v[8:9], v[18:19] op_sel_hi:[1,0]
	v_pk_mul_f32 v[12:13], v[12:13], v[18:19] op_sel_hi:[1,0]
	v_pk_mul_f32 v[10:11], v[10:11], v[18:19] op_sel_hi:[1,0]
	v_pk_mul_f32 v[0:1], v[0:1], v[18:19] op_sel_hi:[1,0]
	v_pk_mul_f32 v[14:15], v[14:15], v[18:19] op_sel_hi:[1,0]
	v_pk_mul_f32 v[4:5], v[4:5], v[18:19] op_sel_hi:[1,0]
	v_pk_mul_f32 v[2:3], v[2:3], v[18:19] op_sel_hi:[1,0]
	v_mul_f32_e32 v18, 0xbfb8aa3b, v17
	v_mul_f32_e32 v19, 0xbfb8aa3b, v9
	v_mul_f32_e32 v20, 0xbfb8aa3b, v13
	v_mul_f32_e32 v21, 0xbfb8aa3b, v11
	v_mul_f32_e32 v23, 0xbfb8aa3b, v1
	v_mul_f32_e32 v22, 0xbfb8aa3b, v15
	v_mul_f32_e32 v24, 0xbfb8aa3b, v5
	v_mul_f32_e32 v25, 0xbfb8aa3b, v3
	v_exp_f32_e32 v18, v18
	v_exp_f32_e32 v19, v19
	v_exp_f32_e32 v20, v20
	v_exp_f32_e32 v21, v21
	v_exp_f32_e32 v23, v23
	v_exp_f32_e32 v22, v22
	v_exp_f32_e32 v24, v24
	v_exp_f32_e32 v25, v25
	v_add_f32_e32 v18, 1.0, v18
	v_add_f32_e32 v19, 1.0, v19
	v_add_f32_e32 v20, 1.0, v20
	v_add_f32_e32 v21, 1.0, v21
	v_add_f32_e32 v23, 1.0, v23
	v_add_f32_e32 v22, 1.0, v22
	v_add_f32_e32 v24, 1.0, v24
	v_add_f32_e32 v25, 1.0, v25
	v_rcp_f32_e32 v18, v18
	v_rcp_f32_e32 v19, v19
	v_rcp_f32_e32 v20, v20
	v_rcp_f32_e32 v21, v21
	v_rcp_f32_e32 v23, v23
	v_rcp_f32_e32 v22, v22
	v_rcp_f32_e32 v24, v24
	v_rcp_f32_e32 v25, v25
	v_mul_f32_e32 v17, v17, v18
	v_mul_f32_e32 v9, v9, v19
	v_mul_f32_e32 v13, v13, v20
	v_mul_f32_e32 v11, v11, v21
	v_mul_f32_e32 v1, v1, v23
	v_mul_f32_e32 v15, v15, v22
	v_mul_f32_e32 v5, v5, v24
	v_mul_f32_e32 v3, v3, v25
	v_mul_f32_e32 v16, v16, v17
	v_mul_f32_e32 v8, v8, v9
	v_mul_f32_e32 v9, v12, v13
	v_mul_f32_e32 v10, v10, v11
	v_mul_f32_e32 v12, v0, v1
	v_cvt_pk_bf16_f32 v0, v16, v8
	v_cvt_pk_bf16_f32 v1, v9, v10
	s_mov_b64 s[4:5], -1
	v_mul_f32_e32 v11, v14, v15
	v_mul_f32_e32 v4, v4, v5
	v_mul_f32_e32 v2, v2, v3
	global_store_dwordx2 v[6:7], v[0:1], off
	v_cvt_pk_bf16_f32 v0, v11, v12
	v_cvt_pk_bf16_f32 v1, v4, v2
	global_store_dwordx2 v[6:7], v[0:1], off offset:128
	s_cbranch_vccnz .LBB0_1045
	s_andn2_b64 vcc, exec, s[18:19]
	s_cbranch_vccnz .LBB0_1044
	s_barrier
	s_branch .LBB0_1044
